# phase-merged GEMM K-loops (4 instances), prologue wait widened to cover SB(0,1) staging
# speedup vs baseline: 1.0227x; 1.0145x over previous
.LBB0_38:
	s_and_b64 s[22:23], s[36:37], exec
	v_readlane_b32 s22, v254, 35
	v_readlane_b32 s40, v254, 37
	v_readlane_b32 s42, v254, 39
	v_readlane_b32 s23, v254, 36
	v_readlane_b32 s41, v254, 38
	v_readlane_b32 s43, v254, 40
	s_cselect_b32 s37, s23, s9
	s_cselect_b32 s36, s22, s8
	s_cselect_b32 s23, s43, s41
	s_cselect_b32 s22, s42, s40
	s_cselect_b32 s45, s41, s43
	s_cselect_b32 s44, s40, s42
	s_and_b32 s63, s20, 3
	s_add_i32 m0, s59, 0x18000
	v_lshl_add_u64 v[8:9], v[8:9], 0, s[12:13]
	s_lshl_b32 s1, s4, 13
	s_lshl_b32 s33, s63, 12
	s_waitcnt vmcnt(2)
	s_barrier
	global_load_lds_dwordx4 v[8:9], off
	v_lshl_add_u64 v[6:7], v[6:7], 0, s[12:13]
	s_add_i32 m0, s59, 0x1a000
	s_add_i32 s64, s59, 0x8000
	s_add_i32 s65, s59, 0xa000
	global_load_lds_dwordx4 v[6:7], off
	v_lshl_add_u64 v[4:5], v[4:5], 0, s[12:13]
	s_mov_b32 m0, s64
	s_add_u32 s20, s30, 0x40080
	global_load_lds_dwordx4 v[4:5], off
	v_lshl_add_u64 v[2:3], v[2:3], 0, s[12:13]
	s_mov_b32 m0, s65
	s_addc_u32 s21, s31, 0
	global_load_lds_dwordx4 v[2:3], off
	s_add_i32 m0, s59, 0x1c000
	v_lshl_add_u64 v[2:3], s[20:21], 0, v[0:1]
	global_load_lds_dwordx4 v[2:3], off
	v_lshl_add_u64 v[2:3], s[20:21], 0, v[154:155]
	s_add_i32 m0, s59, 0x1e000
	v_bfe_u32 v4, v10, 4, 2
	global_load_lds_dwordx4 v[2:3], off
	v_and_b32_e32 v3, 15, v10
	v_lshlrev_b32_e32 v2, 4, v4
	v_lshlrev_b32_e32 v6, 2, v10
	v_lshl_or_b32 v194, s4, 6, v3
	v_lshl_or_b32 v3, v3, 6, v2
	v_and_b32_e32 v6, 32, v6
	v_bitop3_b32 v7, v3, s1, v6 bitop3:0xde
	v_bitop3_b32 v195, v3, s33, v6 bitop3:0xde
	v_mov_b32_e32 v3, v1
	v_lshl_add_u64 v[160:161], s[22:23], 0, v[2:3]
	v_lshlrev_b32_e32 v2, 14, v15
	v_and_b32_e32 v2, 0xffff8000, v2
	v_lshl_add_u32 v2, v14, 11, v2
	v_and_b32_e32 v3, 1, v15
	v_lshl_or_b32 v2, v3, 6, v2
	v_lshl_add_u32 v178, v16, 1, v2
	v_lshlrev_b32_e32 v2, 14, v11
	v_and_b32_e32 v2, 0xffff8000, v2
	s_waitcnt vmcnt(6)
	v_lshl_add_u32 v2, v12, 11, v2
	v_and_b32_e32 v3, 1, v11
	v_lshlrev_b32_e32 v5, 3, v4
	v_lshl_or_b32 v2, v3, 6, v2
	v_lshl_or_b32 v196, s63, 5, v5
	s_mov_b32 s66, 0
	v_cmp_eq_u32_e64 s[40:41], 0, v4
	v_mov_b32_e32 v179, v1
	v_lshl_add_u32 v180, v13, 1, v2
	v_mov_b32_e32 v181, v1
	v_add_u32_e32 v197, 0, v7
	v_readlane_b32 s4, v253, 3
	v_readlane_b32 s20, v253, 35
	s_barrier
	v_readlane_b32 s21, v253, 36
	s_branch .LBB0_40

.LBB0_47:
	s_add_u32 s1, s28, 0xfffc0080
	s_addc_u32 s22, s29, -1
	s_add_i32 s23, 0, 0x10000
	v_add_u32_e32 v142, s23, v195
	ds_read_b128 v[130:133], v142
	ds_read_b128 v[134:137], v142 offset:1024
	ds_read_b128 v[138:141], v142 offset:2048
	ds_read_b128 v[142:145], v142 offset:3072
	s_cmp_eq_u32 s69, 12
	s_cselect_b32 s57, s21, s22
	s_cselect_b32 s56, s34, s1
	s_cselect_b32 s31, s47, s68
	s_cselect_b32 s30, s49, s67
	v_lshl_add_u64 v[176:177], s[28:29], 0, v[178:179]
	s_add_i32 m0, s59, 0xc000
	ds_read_b128 v[146:149], v197
	ds_read_b128 v[150:153], v197 offset:1024
	ds_read_b128 v[182:185], v197 offset:2048
	ds_read_b128 v[186:189], v197 offset:3072
	ds_read_b128 v[190:193], v197 offset:4096
	ds_read_b128 v[198:201], v197 offset:5120
	ds_read_b128 v[202:205], v197 offset:6144
	ds_read_b128 v[206:209], v197 offset:7168
	global_load_lds_dwordx4 v[176:177], off
	v_lshl_add_u64 v[176:177], s[28:29], 0, v[180:181]
	s_add_i32 m0, s59, 0xe000
	s_nop 0
	global_load_lds_dwordx4 v[176:177], off
	s_add_i32 s1, 0, 0x14000
	v_add_u32_e32 v168, s1, v195
	ds_read_b128 v[216:219], v168
	ds_read_b128 v[230:233], v168 offset:1024
	ds_read_b128 v[234:237], v168 offset:2048
	ds_read_b128 v[238:241], v168 offset:3072
	s_waitcnt vmcnt(8)
	s_waitcnt lgkmcnt(0)
	s_barrier
	s_setprio 1
	v_mfma_f32_16x16x32_bf16 v[126:129], v[130:133], v[146:149], v[126:129]
	v_mfma_f32_16x16x32_bf16 v[122:125], v[138:141], v[146:149], v[122:125]
	v_mfma_f32_16x16x32_bf16 v[110:113], v[130:133], v[182:185], v[110:113]
	v_mfma_f32_16x16x32_bf16 v[106:109], v[138:141], v[182:185], v[106:109]
	v_mfma_f32_16x16x32_bf16 v[94:97], v[130:133], v[190:193], v[94:97]
	v_mfma_f32_16x16x32_bf16 v[90:93], v[138:141], v[190:193], v[90:93]
	v_mfma_f32_16x16x32_bf16 v[78:81], v[130:133], v[202:205], v[78:81]
	v_mfma_f32_16x16x32_bf16 v[74:77], v[138:141], v[202:205], v[74:77]
	v_mfma_f32_16x16x32_bf16 v[126:129], v[134:137], v[150:153], v[126:129]
	v_mfma_f32_16x16x32_bf16 v[122:125], v[142:145], v[150:153], v[122:125]
	v_mfma_f32_16x16x32_bf16 v[110:113], v[134:137], v[186:189], v[110:113]
	v_mfma_f32_16x16x32_bf16 v[106:109], v[142:145], v[186:189], v[106:109]
	v_mfma_f32_16x16x32_bf16 v[94:97], v[134:137], v[198:201], v[94:97]
	v_mfma_f32_16x16x32_bf16 v[90:93], v[142:145], v[198:201], v[90:93]
	v_mfma_f32_16x16x32_bf16 v[78:81], v[134:137], v[206:209], v[78:81]
	v_mfma_f32_16x16x32_bf16 v[74:77], v[142:145], v[206:209], v[74:77]
	v_mfma_f32_16x16x32_bf16 v[118:121], v[216:219], v[146:149], v[118:121]
	v_mfma_f32_16x16x32_bf16 v[114:117], v[234:237], v[146:149], v[114:117]
	v_mfma_f32_16x16x32_bf16 v[102:105], v[216:219], v[182:185], v[102:105]
	v_mfma_f32_16x16x32_bf16 v[98:101], v[234:237], v[182:185], v[98:101]
	v_mfma_f32_16x16x32_bf16 v[86:89], v[216:219], v[190:193], v[86:89]
	v_mfma_f32_16x16x32_bf16 v[82:85], v[234:237], v[190:193], v[82:85]
	v_mfma_f32_16x16x32_bf16 v[70:73], v[216:219], v[202:205], v[70:73]
	v_mfma_f32_16x16x32_bf16 v[66:69], v[234:237], v[202:205], v[66:69]
	v_mfma_f32_16x16x32_bf16 v[118:121], v[230:233], v[150:153], v[118:121]
	v_mfma_f32_16x16x32_bf16 v[114:117], v[238:241], v[150:153], v[114:117]
	v_mfma_f32_16x16x32_bf16 v[102:105], v[230:233], v[186:189], v[102:105]
	v_mfma_f32_16x16x32_bf16 v[98:101], v[238:241], v[186:189], v[98:101]
	v_mfma_f32_16x16x32_bf16 v[86:89], v[230:233], v[198:201], v[86:89]
	v_mfma_f32_16x16x32_bf16 v[82:85], v[238:241], v[198:201], v[82:85]
	v_mfma_f32_16x16x32_bf16 v[70:73], v[230:233], v[206:209], v[70:73]
	v_mfma_f32_16x16x32_bf16 v[66:69], v[238:241], v[206:209], v[66:69]
	s_setprio 0
	s_barrier
	ds_read_b128 v[146:149], v197 offset:16384
	ds_read_b128 v[150:153], v197 offset:17408
	ds_read_b128 v[182:185], v197 offset:18432
	ds_read_b128 v[186:189], v197 offset:19456
	ds_read_b128 v[190:193], v197 offset:20480
	ds_read_b128 v[198:201], v197 offset:21504
	ds_read_b128 v[202:205], v197 offset:22528
	ds_read_b128 v[206:209], v197 offset:23552
	s_add_i32 s22, s23, s58
	v_lshl_add_u64 v[176:177], s[30:31], 0, v[0:1]
	s_mov_b32 m0, s22
	s_nop 0
	global_load_lds_dwordx4 v[176:177], off
	v_lshl_add_u64 v[220:221], s[30:31], 0, v[154:155]
	s_add_i32 m0, s22, 0x2000
	s_nop 0
	global_load_lds_dwordx4 v[220:221], off
	s_mov_b32 m0, s59
	v_lshl_add_u64 v[242:243], s[56:57], 0, v[158:159]
	global_load_lds_dwordx4 v[242:243], off
	v_lshl_add_u64 v[244:245], s[56:57], 0, v[156:157]
	s_mov_b32 m0, s60
	s_nop 0
	global_load_lds_dwordx4 v[244:245], off
	s_add_u32 s22, s30, 0x40000
	s_addc_u32 s23, s31, 0
	s_add_i32 s1, s1, s58
	s_mov_b32 m0, s1
	s_nop 0
	global_load_lds_dwordx4 v0, s[22:23]
	s_add_i32 m0, s1, 0x2000
	s_nop 0
	global_load_lds_dwordx4 v154, s[22:23]
	s_waitcnt vmcnt(8)
	s_waitcnt lgkmcnt(0)
	s_barrier
	s_setprio 1
	v_mfma_f32_16x16x32_bf16 v[62:65], v[130:133], v[146:149], v[62:65]
	v_mfma_f32_16x16x32_bf16 v[58:61], v[138:141], v[146:149], v[58:61]
	v_mfma_f32_16x16x32_bf16 v[46:49], v[130:133], v[182:185], v[46:49]
	v_mfma_f32_16x16x32_bf16 v[42:45], v[138:141], v[182:185], v[42:45]
	v_mfma_f32_16x16x32_bf16 v[30:33], v[130:133], v[190:193], v[30:33]
	v_mfma_f32_16x16x32_bf16 v[26:29], v[138:141], v[190:193], v[26:29]
	v_mfma_f32_16x16x32_bf16 v[14:17], v[130:133], v[202:205], v[14:17]
	v_mfma_f32_16x16x32_bf16 v[10:13], v[138:141], v[202:205], v[10:13]
	v_mfma_f32_16x16x32_bf16 v[62:65], v[134:137], v[150:153], v[62:65]
	v_mfma_f32_16x16x32_bf16 v[58:61], v[142:145], v[150:153], v[58:61]
	v_mfma_f32_16x16x32_bf16 v[46:49], v[134:137], v[186:189], v[46:49]
	v_mfma_f32_16x16x32_bf16 v[42:45], v[142:145], v[186:189], v[42:45]
	v_mfma_f32_16x16x32_bf16 v[30:33], v[134:137], v[198:201], v[30:33]
	v_mfma_f32_16x16x32_bf16 v[26:29], v[142:145], v[198:201], v[26:29]
	v_mfma_f32_16x16x32_bf16 v[14:17], v[134:137], v[206:209], v[14:17]
	v_mfma_f32_16x16x32_bf16 v[10:13], v[142:145], v[206:209], v[10:13]
	v_mfma_f32_16x16x32_bf16 v[54:57], v[216:219], v[146:149], v[54:57]
	v_mfma_f32_16x16x32_bf16 v[50:53], v[234:237], v[146:149], v[50:53]
	v_mfma_f32_16x16x32_bf16 v[38:41], v[216:219], v[182:185], v[38:41]
	v_mfma_f32_16x16x32_bf16 v[34:37], v[234:237], v[182:185], v[34:37]
	v_mfma_f32_16x16x32_bf16 v[22:25], v[216:219], v[190:193], v[22:25]
	v_mfma_f32_16x16x32_bf16 v[18:21], v[234:237], v[190:193], v[18:21]
	v_mfma_f32_16x16x32_bf16 v[6:9], v[216:219], v[202:205], v[6:9]
	v_mfma_f32_16x16x32_bf16 v[2:5], v[234:237], v[202:205], v[2:5]
	v_mfma_f32_16x16x32_bf16 v[54:57], v[230:233], v[150:153], v[54:57]
	v_mfma_f32_16x16x32_bf16 v[50:53], v[238:241], v[150:153], v[50:53]
	v_mfma_f32_16x16x32_bf16 v[38:41], v[230:233], v[186:189], v[38:41]
	v_mfma_f32_16x16x32_bf16 v[34:37], v[238:241], v[186:189], v[34:37]
	v_mfma_f32_16x16x32_bf16 v[22:25], v[230:233], v[198:201], v[22:25]
	v_mfma_f32_16x16x32_bf16 v[18:21], v[238:241], v[198:201], v[18:21]
	v_mfma_f32_16x16x32_bf16 v[6:9], v[230:233], v[206:209], v[6:9]
	v_mfma_f32_16x16x32_bf16 v[2:5], v[238:241], v[206:209], v[2:5]
	s_setprio 0
	s_barrier
	s_add_i32 s1, 0, 0x18000
	v_add_u32_e32 v142, s1, v195
	ds_read_b128 v[130:133], v142
	ds_read_b128 v[134:137], v142 offset:1024
	ds_read_b128 v[138:141], v142 offset:2048
	ds_read_b128 v[142:145], v142 offset:3072
	s_add_u32 s22, s56, 0x40000
	s_addc_u32 s23, s57, 0
	s_mov_b32 m0, s61
	v_lshl_add_u64 v[216:217], s[22:23], 0, v[158:159]
	ds_read_b128 v[146:149], v197 offset:32768
	ds_read_b128 v[150:153], v197 offset:33792
	ds_read_b128 v[182:185], v197 offset:34816
	ds_read_b128 v[186:189], v197 offset:35840
	ds_read_b128 v[190:193], v197 offset:36864
	ds_read_b128 v[198:201], v197 offset:37888
	ds_read_b128 v[202:205], v197 offset:38912
	ds_read_b128 v[206:209], v197 offset:39936
	global_load_lds_dwordx4 v[216:217], off
	v_lshl_add_u64 v[216:217], s[22:23], 0, v[156:157]
	s_mov_b32 m0, s62
	s_nop 0
	global_load_lds_dwordx4 v[216:217], off
	s_add_i32 s33, 0, 0x1c000
	v_add_u32_e32 v168, s33, v195
	ds_read_b128 v[216:219], v168
	ds_read_b128 v[230:233], v168 offset:1024
	ds_read_b128 v[234:237], v168 offset:2048
	ds_read_b128 v[238:241], v168 offset:3072
	s_waitcnt vmcnt(8)
	s_waitcnt lgkmcnt(0)
	s_barrier
	s_setprio 1
	v_mfma_f32_16x16x32_bf16 v[126:129], v[130:133], v[146:149], v[126:129]
	v_mfma_f32_16x16x32_bf16 v[122:125], v[138:141], v[146:149], v[122:125]
	v_mfma_f32_16x16x32_bf16 v[110:113], v[130:133], v[182:185], v[110:113]
	v_mfma_f32_16x16x32_bf16 v[106:109], v[138:141], v[182:185], v[106:109]
	v_mfma_f32_16x16x32_bf16 v[94:97], v[130:133], v[190:193], v[94:97]
	v_mfma_f32_16x16x32_bf16 v[90:93], v[138:141], v[190:193], v[90:93]
	v_mfma_f32_16x16x32_bf16 v[78:81], v[130:133], v[202:205], v[78:81]
	v_mfma_f32_16x16x32_bf16 v[74:77], v[138:141], v[202:205], v[74:77]
	v_mfma_f32_16x16x32_bf16 v[126:129], v[134:137], v[150:153], v[126:129]
	v_mfma_f32_16x16x32_bf16 v[122:125], v[142:145], v[150:153], v[122:125]
	v_mfma_f32_16x16x32_bf16 v[110:113], v[134:137], v[186:189], v[110:113]
	v_mfma_f32_16x16x32_bf16 v[106:109], v[142:145], v[186:189], v[106:109]
	v_mfma_f32_16x16x32_bf16 v[94:97], v[134:137], v[198:201], v[94:97]
	v_mfma_f32_16x16x32_bf16 v[90:93], v[142:145], v[198:201], v[90:93]
	v_mfma_f32_16x16x32_bf16 v[78:81], v[134:137], v[206:209], v[78:81]
	v_mfma_f32_16x16x32_bf16 v[74:77], v[142:145], v[206:209], v[74:77]
	v_mfma_f32_16x16x32_bf16 v[118:121], v[216:219], v[146:149], v[118:121]
	v_mfma_f32_16x16x32_bf16 v[114:117], v[234:237], v[146:149], v[114:117]
	v_mfma_f32_16x16x32_bf16 v[102:105], v[216:219], v[182:185], v[102:105]
	v_mfma_f32_16x16x32_bf16 v[98:101], v[234:237], v[182:185], v[98:101]
	v_mfma_f32_16x16x32_bf16 v[86:89], v[216:219], v[190:193], v[86:89]
	v_mfma_f32_16x16x32_bf16 v[82:85], v[234:237], v[190:193], v[82:85]
	v_mfma_f32_16x16x32_bf16 v[70:73], v[216:219], v[202:205], v[70:73]
	v_mfma_f32_16x16x32_bf16 v[66:69], v[234:237], v[202:205], v[66:69]
	v_mfma_f32_16x16x32_bf16 v[118:121], v[230:233], v[150:153], v[118:121]
	v_mfma_f32_16x16x32_bf16 v[114:117], v[238:241], v[150:153], v[114:117]
	v_mfma_f32_16x16x32_bf16 v[102:105], v[230:233], v[186:189], v[102:105]
	v_mfma_f32_16x16x32_bf16 v[98:101], v[238:241], v[186:189], v[98:101]
	v_mfma_f32_16x16x32_bf16 v[86:89], v[230:233], v[198:201], v[86:89]
	v_mfma_f32_16x16x32_bf16 v[82:85], v[238:241], v[198:201], v[82:85]
	v_mfma_f32_16x16x32_bf16 v[70:73], v[230:233], v[206:209], v[70:73]
	v_mfma_f32_16x16x32_bf16 v[66:69], v[238:241], v[206:209], v[66:69]
	s_setprio 0
	s_barrier
	ds_read_b128 v[146:149], v197 offset:49152
	ds_read_b128 v[150:153], v197 offset:50176
	ds_read_b128 v[182:185], v197 offset:51200
	ds_read_b128 v[186:189], v197 offset:52224
	ds_read_b128 v[190:193], v197 offset:53248
	ds_read_b128 v[198:201], v197 offset:54272
	ds_read_b128 v[202:205], v197 offset:55296
	ds_read_b128 v[206:209], v197 offset:56320
	s_add_i32 s1, s1, s58
	v_lshl_add_u64 v[176:177], v[176:177], 0, s[12:13]
	s_mov_b32 m0, s1
	s_nop 0
	global_load_lds_dwordx4 v[176:177], off
	v_lshl_add_u64 v[176:177], v[220:221], 0, s[12:13]
	s_add_i32 m0, s1, 0x2000
	s_nop 0
	global_load_lds_dwordx4 v[176:177], off
	s_mov_b32 m0, s64
	v_lshl_add_u64 v[176:177], v[242:243], 0, s[12:13]
	global_load_lds_dwordx4 v[176:177], off
	v_lshl_add_u64 v[176:177], v[244:245], 0, s[12:13]
	s_mov_b32 m0, s65
	s_nop 0
	global_load_lds_dwordx4 v[176:177], off
	s_add_u32 s22, s30, 0x40080
	s_addc_u32 s23, s31, 0
	s_add_i32 s1, s33, s58
	s_mov_b32 m0, s1
	s_nop 0
	global_load_lds_dwordx4 v0, s[22:23]
	s_add_i32 m0, s1, 0x2000
	s_nop 0
	global_load_lds_dwordx4 v154, s[22:23]
	s_waitcnt vmcnt(8)
	s_waitcnt lgkmcnt(0)
	s_barrier
	s_setprio 1
	v_mfma_f32_16x16x32_bf16 v[62:65], v[130:133], v[146:149], v[62:65]
	v_mfma_f32_16x16x32_bf16 v[58:61], v[138:141], v[146:149], v[58:61]
	v_mfma_f32_16x16x32_bf16 v[46:49], v[130:133], v[182:185], v[46:49]
	v_mfma_f32_16x16x32_bf16 v[42:45], v[138:141], v[182:185], v[42:45]
	v_mfma_f32_16x16x32_bf16 v[30:33], v[130:133], v[190:193], v[30:33]
	v_mfma_f32_16x16x32_bf16 v[26:29], v[138:141], v[190:193], v[26:29]
	v_mfma_f32_16x16x32_bf16 v[14:17], v[130:133], v[202:205], v[14:17]
	v_mfma_f32_16x16x32_bf16 v[10:13], v[138:141], v[202:205], v[10:13]
	v_mfma_f32_16x16x32_bf16 v[62:65], v[134:137], v[150:153], v[62:65]
	v_mfma_f32_16x16x32_bf16 v[58:61], v[142:145], v[150:153], v[58:61]
	v_mfma_f32_16x16x32_bf16 v[46:49], v[134:137], v[186:189], v[46:49]
	v_mfma_f32_16x16x32_bf16 v[42:45], v[142:145], v[186:189], v[42:45]
	v_mfma_f32_16x16x32_bf16 v[30:33], v[134:137], v[198:201], v[30:33]
	v_mfma_f32_16x16x32_bf16 v[26:29], v[142:145], v[198:201], v[26:29]
	v_mfma_f32_16x16x32_bf16 v[14:17], v[134:137], v[206:209], v[14:17]
	v_mfma_f32_16x16x32_bf16 v[10:13], v[142:145], v[206:209], v[10:13]
	v_mfma_f32_16x16x32_bf16 v[54:57], v[216:219], v[146:149], v[54:57]
	v_mfma_f32_16x16x32_bf16 v[50:53], v[234:237], v[146:149], v[50:53]
	v_mfma_f32_16x16x32_bf16 v[38:41], v[216:219], v[182:185], v[38:41]
	v_mfma_f32_16x16x32_bf16 v[34:37], v[234:237], v[182:185], v[34:37]
	v_mfma_f32_16x16x32_bf16 v[22:25], v[216:219], v[190:193], v[22:25]
	v_mfma_f32_16x16x32_bf16 v[18:21], v[234:237], v[190:193], v[18:21]
	v_mfma_f32_16x16x32_bf16 v[6:9], v[216:219], v[202:205], v[6:9]
	v_mfma_f32_16x16x32_bf16 v[2:5], v[234:237], v[202:205], v[2:5]
	v_mfma_f32_16x16x32_bf16 v[54:57], v[230:233], v[150:153], v[54:57]
	v_mfma_f32_16x16x32_bf16 v[50:53], v[238:241], v[150:153], v[50:53]
	v_mfma_f32_16x16x32_bf16 v[38:41], v[230:233], v[186:189], v[38:41]
	v_mfma_f32_16x16x32_bf16 v[34:37], v[238:241], v[186:189], v[34:37]
	v_mfma_f32_16x16x32_bf16 v[22:25], v[230:233], v[198:201], v[22:25]
	v_mfma_f32_16x16x32_bf16 v[18:21], v[238:241], v[198:201], v[18:21]
	v_mfma_f32_16x16x32_bf16 v[6:9], v[230:233], v[206:209], v[6:9]
	v_mfma_f32_16x16x32_bf16 v[2:5], v[238:241], v[206:209], v[2:5]
	s_setprio 0
	s_add_i32 s69, s69, 2
	s_add_u32 s28, s28, 0x100
	s_addc_u32 s29, s29, 0
	s_add_u32 s67, s67, 0x100
	s_addc_u32 s68, s68, 0
	s_cmp_gt_u32 s69, 13
	s_barrier
	s_cbranch_scc0 .LBB0_47
	v_lshl_add_u32 v184, s20, 8, v194
	v_ashrrev_i32_e32 v185, 31, v184
	v_or_b32_e32 v188, 16, v184
	v_lshlrev_b64 v[190:191], 6, v[184:185]
	v_ashrrev_i32_e32 v189, 31, v188
	v_lshl_add_u64 v[130:131], v[160:161], 0, v[190:191]
	v_lshlrev_b64 v[186:187], 6, v[188:189]
	global_load_dwordx4 v[200:203], v[130:131], off
	v_lshl_add_u64 v[130:131], v[160:161], 0, v[186:187]
	global_load_dwordx4 v[204:207], v[130:131], off
	v_lshl_or_b32 v182, s4, 8, v196
	v_ashrrev_i32_e32 v183, 31, v182
	v_lshlrev_b64 v[130:131], 10, v[184:185]
	v_lshl_add_u64 v[130:131], v[130:131], 0, v[182:183]
	v_lshlrev_b64 v[130:131], 1, v[130:131]
	v_lshl_add_u64 v[132:133], s[96:97], 0, v[130:131]
	global_load_dwordx4 v[216:219], v[132:133], off
	global_load_dwordx4 v[146:149], v[132:133], off offset:256
	v_lshl_add_u64 v[134:135], s[24:25], 0, v[130:131]
	global_load_dwordx4 v[230:233], v[134:135], off
	v_and_b32_e32 v135, 64, v212
	v_xor_b32_e32 v134, 16, v212
	v_add_u32_e32 v135, 64, v135
	v_xor_b32_e32 v136, 32, v212
	v_cmp_lt_i32_e32 vcc, v134, v135
	v_or_b32_e32 v130, 0x100, v130
	v_lshl_add_u64 v[130:131], s[24:25], 0, v[130:131]
	v_cndmask_b32_e32 v134, v212, v134, vcc
	v_cmp_lt_i32_e32 vcc, v136, v135
	v_lshlrev_b32_e32 v199, 2, v134
	s_mov_b32 s20, 0x3a800000
	v_cndmask_b32_e32 v135, v212, v136, vcc
	v_lshlrev_b32_e32 v198, 2, v135
	v_lshlrev_b64 v[134:135], 10, v[188:189]
	v_lshl_add_u64 v[134:135], v[134:135], 0, v[182:183]
	v_lshlrev_b64 v[134:135], 1, v[134:135]
	v_lshl_add_u64 v[132:133], s[96:97], 0, v[134:135]
	global_load_dwordx4 v[150:153], v[130:131], off
	global_load_dwordx4 v[138:141], v[132:133], off
	s_nop 0
	global_load_dwordx4 v[130:133], v[132:133], off offset:256
	v_lshl_add_u64 v[136:137], s[24:25], 0, v[134:135]
	v_or_b32_e32 v134, 0x100, v134
	v_lshl_add_u64 v[134:135], s[24:25], 0, v[134:135]
	global_load_dwordx4 v[142:145], v[136:137], off
	s_nop 0
	global_load_dwordx4 v[134:137], v[134:135], off
	s_lshl_b32 s28, s4, 2
	s_ashr_i32 s29, s28, 31
	s_waitcnt vmcnt(0)
	v_mov_b32_e32 v176, v201
	v_mov_b32_e32 v177, v202
	v_mov_b32_e32 v201, v203
	v_mov_b32_e32 v192, v205
	v_mov_b32_e32 v193, v206
	v_mov_b32_e32 v205, v207
	v_pk_add_f32 v[176:177], v[176:177], v[200:201]
	v_pk_add_f32 v[192:193], v[192:193], v[204:205]
	v_mov_b32_e32 v201, v176
	v_mov_b32_e32 v200, v192
	v_mov_b32_e32 v176, v193
	v_pk_add_f32 v[176:177], v[200:201], v[176:177]
	ds_bpermute_b32 v193, v199, v177
	ds_bpermute_b32 v192, v199, v176
	v_lshlrev_b32_e32 v208, 16, v218
	v_and_b32_e32 v209, 0xffff0000, v218
	v_lshlrev_b32_e32 v202, 16, v216
	v_and_b32_e32 v203, 0xffff0000, v216
	s_waitcnt lgkmcnt(0)
	v_pk_add_f32 v[176:177], v[176:177], v[192:193]
	ds_bpermute_b32 v193, v198, v177
	ds_bpermute_b32 v192, v198, v176
	v_lshlrev_b32_e32 v204, 16, v230
	v_and_b32_e32 v205, 0xffff0000, v230
	v_lshlrev_b32_e32 v200, 16, v217
	v_and_b32_e32 v201, 0xffff0000, v217
	s_waitcnt lgkmcnt(0)
	v_pk_add_f32 v[176:177], v[176:177], v[192:193]
	v_lshlrev_b32_e32 v206, 16, v231
	v_pk_fma_f32 v[192:193], v[176:177], s[20:21], v[166:167] op_sel_hi:[1,0,0]
	v_lshlrev_b32_e32 v176, 16, v219
	v_mul_f32_e32 v168, 0x4b800000, v193
	v_cmp_gt_f32_e32 vcc, s39, v193
	v_and_b32_e32 v177, 0xffff0000, v219
	v_and_b32_e32 v207, 0xffff0000, v231
	v_cndmask_b32_e32 v168, v193, v168, vcc
	v_rsq_f32_e32 v168, v168
	v_lshlrev_b32_e32 v216, 16, v232
	v_and_b32_e32 v217, 0xffff0000, v232
	v_mul_f32_e32 v169, 0x45800000, v168
	v_cndmask_b32_e32 v218, v168, v169, vcc
	v_pk_mul_f32 v[126:127], v[126:127], v[218:219] op_sel_hi:[1,0]
	v_pk_mul_f32 v[128:129], v[128:129], v[218:219] op_sel_hi:[1,0]
	v_pk_mul_f32 v[122:123], v[122:123], v[218:219] op_sel_hi:[1,0]
	v_mul_f32_e32 v126, 0xbfb8aa3b, v126
	v_mul_f32_e32 v127, 0xbfb8aa3b, v127
	v_pk_mul_f32 v[124:125], v[124:125], v[218:219] op_sel_hi:[1,0]
	v_mul_f32_e32 v128, 0xbfb8aa3b, v128
	v_mul_f32_e32 v129, 0xbfb8aa3b, v129
	v_mul_f32_e32 v122, 0xbfb8aa3b, v122
	v_mul_f32_e32 v123, 0xbfb8aa3b, v123
	v_exp_f32_e32 v126, v126
	v_exp_f32_e32 v127, v127
	v_mul_f32_e32 v124, 0xbfb8aa3b, v124
	v_mul_f32_e32 v125, 0xbfb8aa3b, v125
	v_exp_f32_e32 v128, v128
	v_exp_f32_e32 v129, v129
	v_exp_f32_e32 v122, v122
	v_exp_f32_e32 v123, v123
	v_exp_f32_e32 v124, v124
	v_exp_f32_e32 v125, v125
	v_add_f32_e32 v126, 1.0, v126
	v_add_f32_e32 v127, 1.0, v127
	v_add_f32_e32 v128, 1.0, v128
	v_add_f32_e32 v129, 1.0, v129
	v_add_f32_e32 v168, 1.0, v122
	v_add_f32_e32 v169, 1.0, v123
	v_rcp_f32_e32 v122, v126
	v_rcp_f32_e32 v123, v127
	v_add_f32_e32 v193, 1.0, v124
	v_add_f32_e32 v219, 1.0, v125
	v_rcp_f32_e32 v124, v128
	v_rcp_f32_e32 v125, v129
	v_rcp_f32_e32 v126, v168
	v_rcp_f32_e32 v127, v169
	v_rcp_f32_e32 v128, v193
	v_rcp_f32_e32 v129, v219
	v_pk_fma_f32 v[122:123], v[122:123], v[204:205], v[202:203]
	v_pk_fma_f32 v[124:125], v[124:125], v[206:207], v[200:201]
	v_pk_fma_f32 v[126:127], v[126:127], v[216:217], v[208:209]
	v_lshlrev_b32_e32 v200, 16, v233
	v_and_b32_e32 v201, 0xffff0000, v233
	v_cvt_pk_bf16_f32 v122, v122, v123
	v_pk_fma_f32 v[128:129], v[128:129], v[200:201], v[176:177]
	v_cvt_pk_bf16_f32 v123, v124, v125
	v_cvt_pk_bf16_f32 v124, v126, v127
	v_and_b32_e32 v127, 0xffff0000, v122
	v_pk_mul_f32 v[118:119], v[118:119], v[218:219] op_sel_hi:[1,0]
	v_cvt_pk_bf16_f32 v125, v128, v129
	v_lshlrev_b32_e32 v126, 16, v122
	v_mul_f32_e32 v127, v127, v127
	v_and_b32_e32 v128, 0xffff0000, v123
	v_mul_f32_e32 v118, 0xbfb8aa3b, v118
	v_mul_f32_e32 v119, 0xbfb8aa3b, v119
	v_fmac_f32_e32 v127, v126, v126
	v_lshlrev_b32_e32 v126, 16, v123
	v_mul_f32_e32 v128, v128, v128
	v_exp_f32_e32 v118, v118
	v_exp_f32_e32 v119, v119
	v_fmac_f32_e32 v128, v126, v126
	v_add_f32_e32 v126, v127, v128
	v_and_b32_e32 v128, 0xffff0000, v124
	v_pk_mul_f32 v[120:121], v[120:121], v[218:219] op_sel_hi:[1,0]
	v_lshlrev_b32_e32 v127, 16, v124
	v_mul_f32_e32 v128, v128, v128
	v_mul_f32_e32 v120, 0xbfb8aa3b, v120
	v_mul_f32_e32 v121, 0xbfb8aa3b, v121
	v_fmac_f32_e32 v128, v127, v127
	v_add_f32_e32 v118, 1.0, v118
	v_add_f32_e32 v119, 1.0, v119
	v_exp_f32_e32 v120, v120
	v_exp_f32_e32 v121, v121
	v_add_f32_e32 v126, v128, v126
	v_and_b32_e32 v128, 0xffff0000, v125
	v_rcp_f32_e32 v118, v118
	v_rcp_f32_e32 v119, v119
	v_lshlrev_b32_e32 v127, 16, v125
	v_mul_f32_e32 v128, v128, v128
	v_pk_mul_f32 v[114:115], v[114:115], v[218:219] op_sel_hi:[1,0]
	v_fmac_f32_e32 v128, v127, v127
	v_mul_f32_e32 v114, 0xbfb8aa3b, v114
	v_add_f32_e32 v168, v128, v126
	v_pk_mul_f32 v[116:117], v[116:117], v[218:219] op_sel_hi:[1,0]
	v_lshlrev_b32_e32 v126, 16, v146
	v_and_b32_e32 v127, 0xffff0000, v146
	v_lshlrev_b32_e32 v128, 16, v150
	v_and_b32_e32 v129, 0xffff0000, v150
	v_add_f32_e32 v120, 1.0, v120
	v_add_f32_e32 v121, 1.0, v121
	v_exp_f32_e32 v146, v114
	v_mul_f32_e32 v114, 0xbfb8aa3b, v115
	v_pk_fma_f32 v[118:119], v[118:119], v[128:129], v[126:127]
	v_rcp_f32_e32 v120, v120
	v_rcp_f32_e32 v121, v121
	v_lshlrev_b32_e32 v126, 16, v147
	v_and_b32_e32 v127, 0xffff0000, v147
	v_exp_f32_e32 v147, v114
	v_mul_f32_e32 v116, 0xbfb8aa3b, v116
	v_mul_f32_e32 v117, 0xbfb8aa3b, v117
	v_exp_f32_e32 v116, v116
	v_exp_f32_e32 v117, v117
	v_lshlrev_b32_e32 v128, 16, v151
	v_and_b32_e32 v129, 0xffff0000, v151
	v_pk_fma_f32 v[114:115], v[120:121], v[128:129], v[126:127]
	v_add_f32_e32 v120, 1.0, v146
	v_add_f32_e32 v121, 1.0, v147
	v_rcp_f32_e32 v120, v120
	v_rcp_f32_e32 v121, v121
	v_add_f32_e32 v116, 1.0, v116
	v_add_f32_e32 v117, 1.0, v117
	v_rcp_f32_e32 v116, v116
	v_rcp_f32_e32 v117, v117
	v_lshlrev_b32_e32 v126, 16, v148
	v_and_b32_e32 v127, 0xffff0000, v148
	v_lshlrev_b32_e32 v128, 16, v152
	v_and_b32_e32 v129, 0xffff0000, v152
	v_pk_fma_f32 v[120:121], v[120:121], v[128:129], v[126:127]
	v_lshlrev_b32_e32 v126, 16, v149
	v_and_b32_e32 v127, 0xffff0000, v149
	v_lshlrev_b32_e32 v128, 16, v153
	v_and_b32_e32 v129, 0xffff0000, v153
	v_pk_fma_f32 v[126:127], v[116:117], v[128:129], v[126:127]
	v_cvt_pk_bf16_f32 v116, v118, v119
	v_cvt_pk_bf16_f32 v117, v114, v115
	v_and_b32_e32 v115, 0xffff0000, v116
	v_lshlrev_b32_e32 v114, 16, v116
	v_mul_f32_e32 v115, v115, v115
	v_cvt_pk_bf16_f32 v118, v120, v121
	v_fmac_f32_e32 v115, v114, v114
	v_and_b32_e32 v120, 0xffff0000, v117
	v_add_f32_e32 v114, v115, v168
	v_lshlrev_b32_e32 v115, 16, v117
	v_mul_f32_e32 v120, v120, v120
	v_fmac_f32_e32 v120, v115, v115
	v_add_f32_e32 v114, v120, v114
	v_and_b32_e32 v120, 0xffff0000, v118
	v_lshlrev_b32_e32 v115, 16, v118
	v_mul_f32_e32 v120, v120, v120
	v_cvt_pk_bf16_f32 v119, v126, v127
	v_fmac_f32_e32 v120, v115, v115
	v_add_f32_e32 v114, v120, v114
	v_and_b32_e32 v120, 0xffff0000, v119
	v_lshlrev_b32_e32 v115, 16, v119
	v_mul_f32_e32 v120, v120, v120
	v_fmac_f32_e32 v120, v115, v115
	v_add_f32_e32 v114, v120, v114
	ds_bpermute_b32 v115, v199, v114
	v_lshlrev_b64 v[120:121], 11, v[184:185]
	v_lshl_add_u64 v[120:121], s[36:37], 0, v[120:121]
	v_cmp_gt_f32_e32 vcc, s39, v192
	v_lshl_add_u64 v[120:121], v[182:183], 1, v[120:121]
	s_waitcnt lgkmcnt(0)
	v_add_f32_e32 v114, v114, v115
	ds_bpermute_b32 v115, v198, v114
	global_store_dwordx4 v[120:121], v[122:125], off
	global_store_dwordx4 v[120:121], v[116:119], off offset:256
	s_and_saveexec_b64 s[30:31], s[40:41]
	s_cbranch_execz .LBB0_50
	v_lshl_add_u64 v[116:117], s[44:45], 0, v[190:191]
	v_lshl_add_u64 v[116:117], s[28:29], 2, v[116:117]
	s_lshl_b32 s4, s63, 2
	v_lshl_add_u64 v[116:117], v[116:117], 0, s[4:5]
	s_waitcnt lgkmcnt(0)
	v_add_f32_e32 v114, v114, v115
	global_store_dword v[116:117], v114, off

.LBB0_79:
	s_and_b64 s[6:7], s[6:7], exec
	v_readlane_b32 s6, v254, 37
	v_readlane_b32 s22, v254, 39
	v_bfe_u32 v20, v16, 4, 2
	v_readlane_b32 s7, v254, 38
	v_readlane_b32 s23, v254, 40
	v_and_b32_e32 v17, 15, v16
	v_lshlrev_b32_e32 v18, 4, v20
	v_lshlrev_b32_e32 v16, 2, v16
	s_cselect_b32 s7, s7, s23
	s_cselect_b32 s6, s6, s22
	v_lshl_or_b32 v199, s21, 6, v17
	v_lshl_or_b32 v17, v17, 6, v18
	s_lshl_b32 s1, s21, 13
	v_and_b32_e32 v16, 32, v16
	v_bitop3_b32 v21, v17, s1, v16 bitop3:0xde
	s_lshl_b32 s1, s20, 5
	s_and_b32 s1, s1, 0x60
	s_lshl_b32 s20, s1, 7
	s_add_i32 m0, s46, 0x18000
	v_lshl_add_u64 v[8:9], v[8:9], 0, s[12:13]
	v_bitop3_b32 v201, v17, s20, v16 bitop3:0xde
	s_waitcnt vmcnt(2)
	s_barrier
	global_load_lds_dwordx4 v[8:9], off
	v_lshl_add_u64 v[6:7], v[6:7], 0, s[12:13]
	s_add_i32 m0, s46, 0x1a000
	s_add_i32 s20, s46, 0x8000
	s_add_i32 s21, s46, 0xa000
	global_load_lds_dwordx4 v[6:7], off
	v_lshl_add_u64 v[4:5], v[4:5], 0, s[12:13]
	s_mov_b32 m0, s20
	s_add_u32 s22, s30, 0x40080
	global_load_lds_dwordx4 v[4:5], off
	v_lshl_add_u64 v[2:3], v[2:3], 0, s[12:13]
	s_mov_b32 m0, s21
	s_addc_u32 s23, s31, 0
	global_load_lds_dwordx4 v[2:3], off
	s_add_i32 m0, s46, 0x1c000
	v_lshl_add_u64 v[2:3], s[22:23], 0, v[0:1]
	global_load_lds_dwordx4 v[2:3], off
	v_lshl_add_u64 v[2:3], s[22:23], 0, v[154:155]
	s_add_i32 m0, s46, 0x1e000
	v_mov_b32_e32 v19, v1
	global_load_lds_dwordx4 v[2:3], off
	v_lshlrev_b32_e32 v2, 14, v14
	v_and_b32_e32 v2, 0xffff8000, v2
	v_lshl_add_u32 v2, v13, 11, v2
	v_and_b32_e32 v3, 1, v14
	v_lshl_or_b32 v2, v3, 6, v2
	v_lshl_add_u32 v178, v15, 1, v2
	v_lshlrev_b32_e32 v2, 14, v10
	v_and_b32_e32 v2, 0xffff8000, v2
	s_waitcnt vmcnt(6)
	v_lshl_add_u32 v2, v11, 11, v2
	v_and_b32_e32 v3, 1, v10
	v_lshl_add_u64 v[160:161], s[6:7], 0, v[18:19]
	v_lshl_or_b32 v2, v3, 6, v2
	v_readlane_b32 s6, v253, 4
	v_lshl_or_b32 v204, v20, 3, s1
	v_mov_b32_e32 v179, v1
	v_lshl_add_u32 v180, v12, 1, v2
	v_mov_b32_e32 v181, v1
	s_mov_b32 s54, 0
	v_add_u32_e32 v205, 0, v21
	v_readlane_b32 s34, v253, 0
	s_mov_b32 s55, s6
	s_barrier
	v_readlane_b32 s7, v253, 5

.LBB0_83:
	s_add_u32 s1, s28, 0xfffc0080
	s_addc_u32 s22, s29, -1
	s_add_i32 s23, 0, 0x10000
	v_add_u32_e32 v142, s23, v201
	ds_read_b128 v[130:133], v142
	ds_read_b128 v[134:137], v142 offset:1024
	ds_read_b128 v[138:141], v142 offset:2048
	ds_read_b128 v[142:145], v142 offset:3072
	s_cmp_eq_u32 s60, 12
	s_cselect_b32 s43, s27, s22
	s_cselect_b32 s42, s56, s1
	s_cselect_b32 s31, s7, s59
	s_cselect_b32 s30, s57, s58
	v_lshl_add_u64 v[176:177], s[28:29], 0, v[178:179]
	s_add_i32 m0, s46, 0xc000
	ds_read_b128 v[146:149], v205
	ds_read_b128 v[150:153], v205 offset:1024
	ds_read_b128 v[182:185], v205 offset:2048
	ds_read_b128 v[186:189], v205 offset:3072
	ds_read_b128 v[190:193], v205 offset:4096
	ds_read_b128 v[194:197], v205 offset:5120
	ds_read_b128 v[206:209], v205 offset:6144
	ds_read_b128 v[216:219], v205 offset:7168
	global_load_lds_dwordx4 v[176:177], off
	v_lshl_add_u64 v[176:177], s[28:29], 0, v[180:181]
	s_add_i32 m0, s46, 0xe000
	s_nop 0
	global_load_lds_dwordx4 v[176:177], off
	s_add_i32 s1, 0, 0x14000
	v_add_u32_e32 v168, s1, v201
	ds_read_b128 v[230:233], v168
	ds_read_b128 v[234:237], v168 offset:1024
	ds_read_b128 v[238:241], v168 offset:2048
	ds_read_b128 v[242:245], v168 offset:3072
	s_waitcnt vmcnt(8)
	s_waitcnt lgkmcnt(0)
	s_barrier
	s_setprio 1
	v_mfma_f32_16x16x32_bf16 v[126:129], v[130:133], v[146:149], v[126:129]
	v_mfma_f32_16x16x32_bf16 v[118:121], v[138:141], v[146:149], v[118:121]
	v_mfma_f32_16x16x32_bf16 v[110:113], v[130:133], v[182:185], v[110:113]
	v_mfma_f32_16x16x32_bf16 v[102:105], v[138:141], v[182:185], v[102:105]
	v_mfma_f32_16x16x32_bf16 v[94:97], v[130:133], v[190:193], v[94:97]
	v_mfma_f32_16x16x32_bf16 v[86:89], v[138:141], v[190:193], v[86:89]
	v_mfma_f32_16x16x32_bf16 v[78:81], v[130:133], v[206:209], v[78:81]
	v_mfma_f32_16x16x32_bf16 v[70:73], v[138:141], v[206:209], v[70:73]
	v_mfma_f32_16x16x32_bf16 v[126:129], v[134:137], v[150:153], v[126:129]
	v_mfma_f32_16x16x32_bf16 v[118:121], v[142:145], v[150:153], v[118:121]
	v_mfma_f32_16x16x32_bf16 v[110:113], v[134:137], v[186:189], v[110:113]
	v_mfma_f32_16x16x32_bf16 v[102:105], v[142:145], v[186:189], v[102:105]
	v_mfma_f32_16x16x32_bf16 v[94:97], v[134:137], v[194:197], v[94:97]
	v_mfma_f32_16x16x32_bf16 v[86:89], v[142:145], v[194:197], v[86:89]
	v_mfma_f32_16x16x32_bf16 v[78:81], v[134:137], v[216:219], v[78:81]
	v_mfma_f32_16x16x32_bf16 v[70:73], v[142:145], v[216:219], v[70:73]
	v_mfma_f32_16x16x32_bf16 v[122:125], v[230:233], v[146:149], v[122:125]
	v_mfma_f32_16x16x32_bf16 v[114:117], v[238:241], v[146:149], v[114:117]
	v_mfma_f32_16x16x32_bf16 v[106:109], v[230:233], v[182:185], v[106:109]
	v_mfma_f32_16x16x32_bf16 v[98:101], v[238:241], v[182:185], v[98:101]
	v_mfma_f32_16x16x32_bf16 v[90:93], v[230:233], v[190:193], v[90:93]
	v_mfma_f32_16x16x32_bf16 v[82:85], v[238:241], v[190:193], v[82:85]
	v_mfma_f32_16x16x32_bf16 v[74:77], v[230:233], v[206:209], v[74:77]
	v_mfma_f32_16x16x32_bf16 v[66:69], v[238:241], v[206:209], v[66:69]
	v_mfma_f32_16x16x32_bf16 v[122:125], v[234:237], v[150:153], v[122:125]
	v_mfma_f32_16x16x32_bf16 v[114:117], v[242:245], v[150:153], v[114:117]
	v_mfma_f32_16x16x32_bf16 v[106:109], v[234:237], v[186:189], v[106:109]
	v_mfma_f32_16x16x32_bf16 v[98:101], v[242:245], v[186:189], v[98:101]
	v_mfma_f32_16x16x32_bf16 v[90:93], v[234:237], v[194:197], v[90:93]
	v_mfma_f32_16x16x32_bf16 v[82:85], v[242:245], v[194:197], v[82:85]
	v_mfma_f32_16x16x32_bf16 v[74:77], v[234:237], v[216:219], v[74:77]
	v_mfma_f32_16x16x32_bf16 v[66:69], v[242:245], v[216:219], v[66:69]
	s_setprio 0
	s_barrier
	ds_read_b128 v[146:149], v205 offset:16384
	ds_read_b128 v[150:153], v205 offset:17408
	ds_read_b128 v[182:185], v205 offset:18432
	ds_read_b128 v[186:189], v205 offset:19456
	ds_read_b128 v[190:193], v205 offset:20480
	ds_read_b128 v[194:197], v205 offset:21504
	ds_read_b128 v[206:209], v205 offset:22528
	ds_read_b128 v[216:219], v205 offset:23552
	s_add_i32 s22, s23, s17
	v_lshl_add_u64 v[176:177], s[30:31], 0, v[0:1]
	s_mov_b32 m0, s22
	s_nop 0
	global_load_lds_dwordx4 v[176:177], off
	v_lshl_add_u64 v[202:203], s[30:31], 0, v[154:155]
	s_add_i32 m0, s22, 0x2000
	s_nop 0
	global_load_lds_dwordx4 v[202:203], off
	s_mov_b32 m0, s46
	v_lshl_add_u64 v[220:221], s[42:43], 0, v[158:159]
	global_load_lds_dwordx4 v[220:221], off
	v_lshl_add_u64 v[246:247], s[42:43], 0, v[156:157]
	s_mov_b32 m0, s47
	s_nop 0
	global_load_lds_dwordx4 v[246:247], off
	s_add_u32 s22, s30, 0x40000
	s_addc_u32 s23, s31, 0
	s_add_i32 s1, s1, s17
	s_mov_b32 m0, s1
	s_nop 0
	global_load_lds_dwordx4 v0, s[22:23]
	s_add_i32 m0, s1, 0x2000
	s_nop 0
	global_load_lds_dwordx4 v154, s[22:23]
	s_waitcnt vmcnt(8)
	s_waitcnt lgkmcnt(0)
	s_barrier
	s_setprio 1
	v_mfma_f32_16x16x32_bf16 v[62:65], v[130:133], v[146:149], v[62:65]
	v_mfma_f32_16x16x32_bf16 v[54:57], v[138:141], v[146:149], v[54:57]
	v_mfma_f32_16x16x32_bf16 v[46:49], v[130:133], v[182:185], v[46:49]
	v_mfma_f32_16x16x32_bf16 v[38:41], v[138:141], v[182:185], v[38:41]
	v_mfma_f32_16x16x32_bf16 v[30:33], v[130:133], v[190:193], v[30:33]
	v_mfma_f32_16x16x32_bf16 v[22:25], v[138:141], v[190:193], v[22:25]
	v_mfma_f32_16x16x32_bf16 v[14:17], v[130:133], v[206:209], v[14:17]
	v_mfma_f32_16x16x32_bf16 v[6:9], v[138:141], v[206:209], v[6:9]
	v_mfma_f32_16x16x32_bf16 v[62:65], v[134:137], v[150:153], v[62:65]
	v_mfma_f32_16x16x32_bf16 v[54:57], v[142:145], v[150:153], v[54:57]
	v_mfma_f32_16x16x32_bf16 v[46:49], v[134:137], v[186:189], v[46:49]
	v_mfma_f32_16x16x32_bf16 v[38:41], v[142:145], v[186:189], v[38:41]
	v_mfma_f32_16x16x32_bf16 v[30:33], v[134:137], v[194:197], v[30:33]
	v_mfma_f32_16x16x32_bf16 v[22:25], v[142:145], v[194:197], v[22:25]
	v_mfma_f32_16x16x32_bf16 v[14:17], v[134:137], v[216:219], v[14:17]
	v_mfma_f32_16x16x32_bf16 v[6:9], v[142:145], v[216:219], v[6:9]
	v_mfma_f32_16x16x32_bf16 v[58:61], v[230:233], v[146:149], v[58:61]
	v_mfma_f32_16x16x32_bf16 v[50:53], v[238:241], v[146:149], v[50:53]
	v_mfma_f32_16x16x32_bf16 v[42:45], v[230:233], v[182:185], v[42:45]
	v_mfma_f32_16x16x32_bf16 v[34:37], v[238:241], v[182:185], v[34:37]
	v_mfma_f32_16x16x32_bf16 v[26:29], v[230:233], v[190:193], v[26:29]
	v_mfma_f32_16x16x32_bf16 v[18:21], v[238:241], v[190:193], v[18:21]
	v_mfma_f32_16x16x32_bf16 v[10:13], v[230:233], v[206:209], v[10:13]
	v_mfma_f32_16x16x32_bf16 v[2:5], v[238:241], v[206:209], v[2:5]
	v_mfma_f32_16x16x32_bf16 v[58:61], v[234:237], v[150:153], v[58:61]
	v_mfma_f32_16x16x32_bf16 v[50:53], v[242:245], v[150:153], v[50:53]
	v_mfma_f32_16x16x32_bf16 v[42:45], v[234:237], v[186:189], v[42:45]
	v_mfma_f32_16x16x32_bf16 v[34:37], v[242:245], v[186:189], v[34:37]
	v_mfma_f32_16x16x32_bf16 v[26:29], v[234:237], v[194:197], v[26:29]
	v_mfma_f32_16x16x32_bf16 v[18:21], v[242:245], v[194:197], v[18:21]
	v_mfma_f32_16x16x32_bf16 v[10:13], v[234:237], v[216:219], v[10:13]
	v_mfma_f32_16x16x32_bf16 v[2:5], v[242:245], v[216:219], v[2:5]
	s_setprio 0
	s_barrier
	s_add_i32 s1, 0, 0x18000
	v_add_u32_e32 v142, s1, v201
	ds_read_b128 v[130:133], v142
	ds_read_b128 v[134:137], v142 offset:1024
	ds_read_b128 v[138:141], v142 offset:2048
	ds_read_b128 v[142:145], v142 offset:3072
	s_add_u32 s22, s42, 0x40000
	s_addc_u32 s23, s43, 0
	s_mov_b32 m0, s48
	v_lshl_add_u64 v[230:231], s[22:23], 0, v[158:159]
	ds_read_b128 v[146:149], v205 offset:32768
	ds_read_b128 v[150:153], v205 offset:33792
	ds_read_b128 v[182:185], v205 offset:34816
	ds_read_b128 v[186:189], v205 offset:35840
	ds_read_b128 v[190:193], v205 offset:36864
	ds_read_b128 v[194:197], v205 offset:37888
	ds_read_b128 v[206:209], v205 offset:38912
	ds_read_b128 v[216:219], v205 offset:39936
	global_load_lds_dwordx4 v[230:231], off
	v_lshl_add_u64 v[230:231], s[22:23], 0, v[156:157]
	s_mov_b32 m0, s49
	s_nop 0
	global_load_lds_dwordx4 v[230:231], off
	s_add_i32 s33, 0, 0x1c000
	v_add_u32_e32 v168, s33, v201
	ds_read_b128 v[230:233], v168
	ds_read_b128 v[234:237], v168 offset:1024
	ds_read_b128 v[238:241], v168 offset:2048
	ds_read_b128 v[242:245], v168 offset:3072
	s_waitcnt vmcnt(8)
	s_waitcnt lgkmcnt(0)
	s_barrier
	s_setprio 1
	v_mfma_f32_16x16x32_bf16 v[126:129], v[130:133], v[146:149], v[126:129]
	v_mfma_f32_16x16x32_bf16 v[118:121], v[138:141], v[146:149], v[118:121]
	v_mfma_f32_16x16x32_bf16 v[110:113], v[130:133], v[182:185], v[110:113]
	v_mfma_f32_16x16x32_bf16 v[102:105], v[138:141], v[182:185], v[102:105]
	v_mfma_f32_16x16x32_bf16 v[94:97], v[130:133], v[190:193], v[94:97]
	v_mfma_f32_16x16x32_bf16 v[86:89], v[138:141], v[190:193], v[86:89]
	v_mfma_f32_16x16x32_bf16 v[78:81], v[130:133], v[206:209], v[78:81]
	v_mfma_f32_16x16x32_bf16 v[70:73], v[138:141], v[206:209], v[70:73]
	v_mfma_f32_16x16x32_bf16 v[126:129], v[134:137], v[150:153], v[126:129]
	v_mfma_f32_16x16x32_bf16 v[118:121], v[142:145], v[150:153], v[118:121]
	v_mfma_f32_16x16x32_bf16 v[110:113], v[134:137], v[186:189], v[110:113]
	v_mfma_f32_16x16x32_bf16 v[102:105], v[142:145], v[186:189], v[102:105]
	v_mfma_f32_16x16x32_bf16 v[94:97], v[134:137], v[194:197], v[94:97]
	v_mfma_f32_16x16x32_bf16 v[86:89], v[142:145], v[194:197], v[86:89]
	v_mfma_f32_16x16x32_bf16 v[78:81], v[134:137], v[216:219], v[78:81]
	v_mfma_f32_16x16x32_bf16 v[70:73], v[142:145], v[216:219], v[70:73]
	v_mfma_f32_16x16x32_bf16 v[122:125], v[230:233], v[146:149], v[122:125]
	v_mfma_f32_16x16x32_bf16 v[114:117], v[238:241], v[146:149], v[114:117]
	v_mfma_f32_16x16x32_bf16 v[106:109], v[230:233], v[182:185], v[106:109]
	v_mfma_f32_16x16x32_bf16 v[98:101], v[238:241], v[182:185], v[98:101]
	v_mfma_f32_16x16x32_bf16 v[90:93], v[230:233], v[190:193], v[90:93]
	v_mfma_f32_16x16x32_bf16 v[82:85], v[238:241], v[190:193], v[82:85]
	v_mfma_f32_16x16x32_bf16 v[74:77], v[230:233], v[206:209], v[74:77]
	v_mfma_f32_16x16x32_bf16 v[66:69], v[238:241], v[206:209], v[66:69]
	v_mfma_f32_16x16x32_bf16 v[122:125], v[234:237], v[150:153], v[122:125]
	v_mfma_f32_16x16x32_bf16 v[114:117], v[242:245], v[150:153], v[114:117]
	v_mfma_f32_16x16x32_bf16 v[106:109], v[234:237], v[186:189], v[106:109]
	v_mfma_f32_16x16x32_bf16 v[98:101], v[242:245], v[186:189], v[98:101]
	v_mfma_f32_16x16x32_bf16 v[90:93], v[234:237], v[194:197], v[90:93]
	v_mfma_f32_16x16x32_bf16 v[82:85], v[242:245], v[194:197], v[82:85]
	v_mfma_f32_16x16x32_bf16 v[74:77], v[234:237], v[216:219], v[74:77]
	v_mfma_f32_16x16x32_bf16 v[66:69], v[242:245], v[216:219], v[66:69]
	s_setprio 0
	s_barrier
	ds_read_b128 v[146:149], v205 offset:49152
	ds_read_b128 v[150:153], v205 offset:50176
	ds_read_b128 v[182:185], v205 offset:51200
	ds_read_b128 v[186:189], v205 offset:52224
	ds_read_b128 v[190:193], v205 offset:53248
	ds_read_b128 v[194:197], v205 offset:54272
	ds_read_b128 v[206:209], v205 offset:55296
	ds_read_b128 v[216:219], v205 offset:56320
	s_add_i32 s1, s1, s17
	v_lshl_add_u64 v[176:177], v[176:177], 0, s[12:13]
	s_mov_b32 m0, s1
	s_nop 0
	global_load_lds_dwordx4 v[176:177], off
	v_lshl_add_u64 v[176:177], v[202:203], 0, s[12:13]
	s_add_i32 m0, s1, 0x2000
	s_nop 0
	global_load_lds_dwordx4 v[176:177], off
	s_mov_b32 m0, s20
	v_lshl_add_u64 v[176:177], v[220:221], 0, s[12:13]
	global_load_lds_dwordx4 v[176:177], off
	v_lshl_add_u64 v[176:177], v[246:247], 0, s[12:13]
	s_mov_b32 m0, s21
	s_nop 0
	global_load_lds_dwordx4 v[176:177], off
	s_add_u32 s22, s30, 0x40080
	s_addc_u32 s23, s31, 0
	s_add_i32 s1, s33, s17
	s_mov_b32 m0, s1
	s_nop 0
	global_load_lds_dwordx4 v0, s[22:23]
	s_add_i32 m0, s1, 0x2000
	s_nop 0
	global_load_lds_dwordx4 v154, s[22:23]
	s_waitcnt vmcnt(8)
	s_waitcnt lgkmcnt(0)
	s_barrier
	s_setprio 1
	v_mfma_f32_16x16x32_bf16 v[62:65], v[130:133], v[146:149], v[62:65]
	v_mfma_f32_16x16x32_bf16 v[54:57], v[138:141], v[146:149], v[54:57]
	v_mfma_f32_16x16x32_bf16 v[46:49], v[130:133], v[182:185], v[46:49]
	v_mfma_f32_16x16x32_bf16 v[38:41], v[138:141], v[182:185], v[38:41]
	v_mfma_f32_16x16x32_bf16 v[30:33], v[130:133], v[190:193], v[30:33]
	v_mfma_f32_16x16x32_bf16 v[22:25], v[138:141], v[190:193], v[22:25]
	v_mfma_f32_16x16x32_bf16 v[14:17], v[130:133], v[206:209], v[14:17]
	v_mfma_f32_16x16x32_bf16 v[6:9], v[138:141], v[206:209], v[6:9]
	v_mfma_f32_16x16x32_bf16 v[62:65], v[134:137], v[150:153], v[62:65]
	v_mfma_f32_16x16x32_bf16 v[54:57], v[142:145], v[150:153], v[54:57]
	v_mfma_f32_16x16x32_bf16 v[46:49], v[134:137], v[186:189], v[46:49]
	v_mfma_f32_16x16x32_bf16 v[38:41], v[142:145], v[186:189], v[38:41]
	v_mfma_f32_16x16x32_bf16 v[30:33], v[134:137], v[194:197], v[30:33]
	v_mfma_f32_16x16x32_bf16 v[22:25], v[142:145], v[194:197], v[22:25]
	v_mfma_f32_16x16x32_bf16 v[14:17], v[134:137], v[216:219], v[14:17]
	v_mfma_f32_16x16x32_bf16 v[6:9], v[142:145], v[216:219], v[6:9]
	v_mfma_f32_16x16x32_bf16 v[58:61], v[230:233], v[146:149], v[58:61]
	v_mfma_f32_16x16x32_bf16 v[50:53], v[238:241], v[146:149], v[50:53]
	v_mfma_f32_16x16x32_bf16 v[42:45], v[230:233], v[182:185], v[42:45]
	v_mfma_f32_16x16x32_bf16 v[34:37], v[238:241], v[182:185], v[34:37]
	v_mfma_f32_16x16x32_bf16 v[26:29], v[230:233], v[190:193], v[26:29]
	v_mfma_f32_16x16x32_bf16 v[18:21], v[238:241], v[190:193], v[18:21]
	v_mfma_f32_16x16x32_bf16 v[10:13], v[230:233], v[206:209], v[10:13]
	v_mfma_f32_16x16x32_bf16 v[2:5], v[238:241], v[206:209], v[2:5]
	v_mfma_f32_16x16x32_bf16 v[58:61], v[234:237], v[150:153], v[58:61]
	v_mfma_f32_16x16x32_bf16 v[50:53], v[242:245], v[150:153], v[50:53]
	v_mfma_f32_16x16x32_bf16 v[42:45], v[234:237], v[186:189], v[42:45]
	v_mfma_f32_16x16x32_bf16 v[34:37], v[242:245], v[186:189], v[34:37]
	v_mfma_f32_16x16x32_bf16 v[26:29], v[234:237], v[194:197], v[26:29]
	v_mfma_f32_16x16x32_bf16 v[18:21], v[242:245], v[194:197], v[18:21]
	v_mfma_f32_16x16x32_bf16 v[10:13], v[234:237], v[216:219], v[10:13]
	v_mfma_f32_16x16x32_bf16 v[2:5], v[242:245], v[216:219], v[2:5]
	s_setprio 0
	s_add_i32 s60, s60, 2
	s_add_u32 s28, s28, 0x100
	s_addc_u32 s29, s29, 0
	s_add_u32 s58, s58, 0x100
	s_addc_u32 s59, s59, 0
	s_cmp_gt_u32 s60, 13
	s_barrier
	s_cbranch_scc0 .LBB0_83
	v_lshl_add_u32 v196, s55, 8, v199
	v_ashrrev_i32_e32 v197, 31, v196
	v_lshlrev_b64 v[130:131], 6, v[196:197]
	v_or_b32_e32 v194, 16, v196
	v_lshl_add_u64 v[130:131], v[160:161], 0, v[130:131]
	v_ashrrev_i32_e32 v195, 31, v194
	global_load_dwordx4 v[206:209], v[130:131], off
	v_lshlrev_b64 v[130:131], 6, v[194:195]
	v_lshl_add_u64 v[130:131], v[160:161], 0, v[130:131]
	global_load_dwordx4 v[216:219], v[130:131], off
	v_or_b32_e32 v192, 32, v196
	v_ashrrev_i32_e32 v193, 31, v192
	v_lshlrev_b64 v[130:131], 6, v[192:193]
	v_or_b32_e32 v190, 48, v196
	v_lshl_add_u64 v[130:131], v[160:161], 0, v[130:131]
	v_ashrrev_i32_e32 v191, 31, v190
	global_load_dwordx4 v[150:153], v[130:131], off
	v_lshlrev_b64 v[130:131], 6, v[190:191]
	v_lshl_add_u64 v[130:131], v[160:161], 0, v[130:131]
	global_load_dwordx4 v[146:149], v[130:131], off
	v_add_u32_e32 v188, 0x80, v196
	v_ashrrev_i32_e32 v189, 31, v188
	v_lshlrev_b64 v[130:131], 6, v[188:189]
	v_add_u32_e32 v186, 0x90, v196
	v_lshl_add_u64 v[130:131], v[160:161], 0, v[130:131]
	v_ashrrev_i32_e32 v187, 31, v186
	global_load_dwordx4 v[142:145], v[130:131], off
	v_lshlrev_b64 v[130:131], 6, v[186:187]
	v_lshl_add_u64 v[130:131], v[160:161], 0, v[130:131]
	global_load_dwordx4 v[138:141], v[130:131], off
	v_add_u32_e32 v184, 0xa0, v196
	v_ashrrev_i32_e32 v185, 31, v184
	v_lshlrev_b64 v[130:131], 6, v[184:185]
	v_add_u32_e32 v182, 0xb0, v196
	v_lshl_add_u64 v[130:131], v[160:161], 0, v[130:131]
	v_ashrrev_i32_e32 v183, 31, v182
	global_load_dwordx4 v[134:137], v[130:131], off
	v_lshlrev_b64 v[130:131], 6, v[182:183]
	v_lshl_add_u64 v[130:131], v[160:161], 0, v[130:131]
	global_load_dwordx4 v[130:133], v[130:131], off
	v_and_b32_e32 v169, 64, v212
	v_xor_b32_e32 v168, 16, v212
	v_add_u32_e32 v169, 64, v169
	v_cmp_lt_i32_e32 vcc, v168, v169
	s_mov_b32 s22, 0x358637bd
	s_mov_b32 s55, s26
	v_cndmask_b32_e32 v168, v212, v168, vcc
	v_lshlrev_b32_e32 v185, 2, v168
	v_xor_b32_e32 v168, 32, v212
	v_cmp_lt_i32_e32 vcc, v168, v169
	s_mov_b64 s[30:31], s[44:45]
	s_mov_b64 s[28:29], s[36:37]
	v_cndmask_b32_e32 v168, v212, v168, vcc
	v_lshlrev_b32_e32 v183, 2, v168
	s_waitcnt vmcnt(0)
	v_mov_b32_e32 v176, v207
	v_mov_b32_e32 v177, v208
	v_mov_b32_e32 v207, v209
	v_mov_b32_e32 v202, v217
	v_mov_b32_e32 v203, v218
	v_mov_b32_e32 v217, v219
	v_pk_add_f32 v[176:177], v[176:177], v[206:207]
	v_pk_add_f32 v[202:203], v[202:203], v[216:217]
	v_mov_b32_e32 v207, v176
	v_mov_b32_e32 v206, v202
	v_mov_b32_e32 v176, v203
	v_pk_add_f32 v[176:177], v[206:207], v[176:177]
	ds_bpermute_b32 v203, v185, v177
	ds_bpermute_b32 v202, v185, v176
	s_waitcnt lgkmcnt(0)
	v_pk_add_f32 v[176:177], v[176:177], v[202:203]
	ds_bpermute_b32 v203, v183, v177
	ds_bpermute_b32 v202, v183, v176
	s_waitcnt lgkmcnt(0)
	v_pk_add_f32 v[176:177], v[176:177], v[202:203]
	v_mov_b64_e32 v[202:203], s[22:23]
	s_mov_b32 s22, 0x3a800000
	v_pk_fma_f32 v[176:177], v[176:177], s[22:23], v[202:203] op_sel_hi:[1,0,0]
	s_nop 0
	v_mul_f32_e32 v168, 0x4b800000, v177
	v_cmp_gt_f32_e64 s[42:43], s39, v177
	v_cmp_gt_f32_e32 vcc, s39, v176
	s_nop 0
	v_cndmask_b32_e64 v168, v177, v168, s[42:43]
	v_rsq_f32_e32 v168, v168
	v_mov_b32_e32 v177, v152
	v_mov_b32_e32 v152, v147
	v_mov_b32_e32 v147, v149
	v_mul_f32_e32 v169, 0x45800000, v168
	v_cndmask_b32_e64 v200, v168, v169, s[42:43]
	v_mul_f32_e32 v168, 0x4b800000, v176
	v_cndmask_b32_e32 v168, v176, v168, vcc
	v_mov_b32_e32 v176, v151
	v_mov_b32_e32 v151, v153
	v_mov_b32_e32 v153, v148
	v_pk_add_f32 v[150:151], v[176:177], v[150:151]
	v_pk_add_f32 v[146:147], v[152:153], v[146:147]
	v_mov_b32_e32 v149, v150
	v_mov_b32_e32 v148, v146
	v_mov_b32_e32 v150, v147
	v_pk_add_f32 v[146:147], v[148:149], v[150:151]
	ds_bpermute_b32 v149, v185, v147
	ds_bpermute_b32 v148, v185, v146
	v_mov_b32_e32 v150, v143
	v_mov_b32_e32 v151, v144
	v_mov_b32_e32 v143, v145
	v_mov_b32_e32 v144, v139
	v_mov_b32_e32 v145, v140
	v_mov_b32_e32 v139, v141
	v_pk_add_f32 v[142:143], v[150:151], v[142:143]
	v_pk_add_f32 v[138:139], v[144:145], v[138:139]
	s_waitcnt lgkmcnt(0)
	v_pk_add_f32 v[146:147], v[146:147], v[148:149]
	v_mov_b32_e32 v140, v138
	v_mov_b32_e32 v141, v142
	v_mov_b32_e32 v142, v139
	ds_bpermute_b32 v149, v183, v147
	ds_bpermute_b32 v148, v183, v146
	v_pk_add_f32 v[138:139], v[140:141], v[142:143]
	ds_bpermute_b32 v141, v185, v139
	ds_bpermute_b32 v140, v185, v138
	v_mov_b32_e32 v142, v135
	v_mov_b32_e32 v143, v136
	v_mov_b32_e32 v135, v137
	v_mov_b32_e32 v136, v131
	v_mov_b32_e32 v137, v132
	v_mov_b32_e32 v131, v133
	s_waitcnt lgkmcnt(2)
	v_pk_add_f32 v[146:147], v[146:147], v[148:149]
	v_pk_add_f32 v[134:135], v[142:143], v[134:135]
	v_pk_add_f32 v[130:131], v[136:137], v[130:131]
	v_pk_fma_f32 v[146:147], v[146:147], s[22:23], v[202:203] op_sel_hi:[1,0,0]
	s_waitcnt lgkmcnt(0)
	v_pk_add_f32 v[138:139], v[138:139], v[140:141]
	v_mov_b32_e32 v132, v130
	v_mov_b32_e32 v133, v134
	v_mov_b32_e32 v134, v131
	v_mul_f32_e32 v148, 0x4b800000, v147
	v_cmp_gt_f32_e64 s[42:43], s39, v147
	ds_bpermute_b32 v141, v183, v139
	ds_bpermute_b32 v140, v183, v138
	v_pk_add_f32 v[130:131], v[132:133], v[134:135]
	v_cndmask_b32_e64 v147, v147, v148, s[42:43]
	ds_bpermute_b32 v133, v185, v131
	ds_bpermute_b32 v132, v185, v130
	v_rsq_f32_e32 v168, v168
	v_rsq_f32_e32 v147, v147
	s_waitcnt lgkmcnt(2)
	v_pk_add_f32 v[138:139], v[138:139], v[140:141]
	v_pk_mul_f32 v[126:127], v[126:127], v[200:201] op_sel_hi:[1,0]
	v_mul_f32_e32 v169, 0x45800000, v168
	v_mul_f32_e32 v148, 0x45800000, v147
	v_pk_fma_f32 v[138:139], v[138:139], s[22:23], v[202:203] op_sel_hi:[1,0,0]
	s_waitcnt lgkmcnt(0)
	v_pk_add_f32 v[130:131], v[130:131], v[132:133]
	v_cndmask_b32_e32 v198, v168, v169, vcc
	v_cmp_gt_f32_e32 vcc, s39, v146
	v_cndmask_b32_e64 v148, v147, v148, s[42:43]
	v_mul_f32_e32 v147, 0x4b800000, v146
	v_mul_f32_e32 v140, 0x4b800000, v139
	v_cmp_gt_f32_e64 s[42:43], s39, v139
	ds_bpermute_b32 v133, v183, v131
	ds_bpermute_b32 v132, v183, v130
	v_cndmask_b32_e32 v146, v146, v147, vcc
	v_cndmask_b32_e64 v139, v139, v140, s[42:43]
	v_rsq_f32_e32 v146, v146
	v_rsq_f32_e32 v139, v139
	s_waitcnt lgkmcnt(0)
	v_pk_add_f32 v[130:131], v[130:131], v[132:133]
	v_pk_mul_f32 v[122:123], v[122:123], v[200:201] op_sel_hi:[1,0]
	v_mul_f32_e32 v147, 0x45800000, v146
	v_mul_f32_e32 v140, 0x45800000, v139
	v_pk_fma_f32 v[130:131], v[130:131], s[22:23], v[202:203] op_sel_hi:[1,0,0]
	v_cndmask_b32_e32 v146, v146, v147, vcc
	v_cmp_gt_f32_e32 vcc, s39, v138
	v_cndmask_b32_e64 v140, v139, v140, s[42:43]
	v_mul_f32_e32 v139, 0x4b800000, v138
	v_mul_f32_e32 v132, 0x4b800000, v131
	v_cmp_gt_f32_e64 s[42:43], s39, v131
	v_cndmask_b32_e32 v138, v138, v139, vcc
	v_rsq_f32_e32 v138, v138
	v_cndmask_b32_e64 v131, v131, v132, s[42:43]
	v_rsq_f32_e32 v131, v131
	v_pk_mul_f32 v[124:125], v[124:125], v[200:201] op_sel_hi:[1,0]
	v_mul_f32_e32 v139, 0x45800000, v138
	v_cndmask_b32_e32 v138, v138, v139, vcc
	v_mul_f32_e32 v132, 0x45800000, v131
	v_cmp_gt_f32_e32 vcc, s39, v130
	v_cndmask_b32_e64 v132, v131, v132, s[42:43]
	v_mul_f32_e32 v131, 0x4b800000, v130
	v_cndmask_b32_e32 v130, v130, v131, vcc
	v_rsq_f32_e32 v130, v130
	v_pk_mul_f32 v[118:119], v[118:119], v[200:201] op_sel_hi:[1,0]
	v_pk_mul_f32 v[114:115], v[114:115], v[200:201] op_sel_hi:[1,0]
	v_lshl_or_b32 v134, s34, 7, v204
	v_mul_f32_e32 v131, 0x45800000, v130
	v_cndmask_b32_e32 v130, v130, v131, vcc
	v_mul_f32_e32 v131, 0xbfb8aa3b, v126
	v_exp_f32_e32 v131, v131
	v_pk_mul_f32 v[116:117], v[116:117], v[200:201] op_sel_hi:[1,0]
	v_ashrrev_i32_e32 v135, 31, v134
	v_pk_mul_f32 v[110:111], v[110:111], v[198:199] op_sel_hi:[1,0]
	v_add_f32_e32 v131, 1.0, v131
	v_rcp_f32_e32 v136, v131
	v_mul_f32_e32 v131, 0xbfb8aa3b, v127
	v_exp_f32_e32 v131, v131
	v_pk_mul_f32 v[106:107], v[106:107], v[198:199] op_sel_hi:[1,0]
	v_pk_mul_f32 v[108:109], v[108:109], v[198:199] op_sel_hi:[1,0]
	v_pk_mul_f32 v[102:103], v[102:103], v[198:199] op_sel_hi:[1,0]
	v_add_f32_e32 v131, 1.0, v131
	v_rcp_f32_e32 v137, v131
	v_pk_mul_f32 v[98:99], v[98:99], v[198:199] op_sel_hi:[1,0]
	v_pk_mul_f32 v[100:101], v[100:101], v[198:199] op_sel_hi:[1,0]
	v_pk_mul_f32 v[94:95], v[94:95], v[148:149] op_sel_hi:[1,0]
	v_pk_mul_f32 v[126:127], v[126:127], v[136:137]
	v_pk_mul_f32 v[90:91], v[90:91], v[148:149] op_sel_hi:[1,0]
	v_pk_mul_f32 v[122:123], v[122:123], v[126:127]
	v_pk_mul_f32 v[126:127], v[128:129], v[200:201] op_sel_hi:[1,0]
	v_cvt_pk_bf16_f32 v122, v122, v123
	v_mul_f32_e32 v128, 0xbfb8aa3b, v126
	v_mul_f32_e32 v129, 0xbfb8aa3b, v127
	v_exp_f32_e32 v128, v128
	v_exp_f32_e32 v129, v129
	v_pk_mul_f32 v[92:93], v[92:93], v[148:149] op_sel_hi:[1,0]
	v_pk_mul_f32 v[86:87], v[86:87], v[148:149] op_sel_hi:[1,0]
	v_add_f32_e32 v128, 1.0, v128
	v_add_f32_e32 v129, 1.0, v129
	v_rcp_f32_e32 v128, v128
	v_rcp_f32_e32 v129, v129
	v_pk_mul_f32 v[82:83], v[82:83], v[148:149] op_sel_hi:[1,0]
	v_pk_mul_f32 v[84:85], v[84:85], v[148:149] op_sel_hi:[1,0]
	v_pk_mul_f32 v[78:79], v[78:79], v[146:147] op_sel_hi:[1,0]
	v_pk_mul_f32 v[126:127], v[126:127], v[128:129]
	v_pk_mul_f32 v[74:75], v[74:75], v[146:147] op_sel_hi:[1,0]
	v_pk_mul_f32 v[124:125], v[124:125], v[126:127]
	v_pk_mul_f32 v[76:77], v[76:77], v[146:147] op_sel_hi:[1,0]
	v_cvt_pk_bf16_f32 v123, v124, v125
	v_mul_f32_e32 v124, 0xbfb8aa3b, v118
	v_mul_f32_e32 v125, 0xbfb8aa3b, v119
	v_exp_f32_e32 v124, v124
	v_exp_f32_e32 v125, v125
	v_pk_mul_f32 v[70:71], v[70:71], v[146:147] op_sel_hi:[1,0]
	v_pk_mul_f32 v[66:67], v[66:67], v[146:147] op_sel_hi:[1,0]
	v_add_f32_e32 v124, 1.0, v124
	v_add_f32_e32 v125, 1.0, v125
	v_rcp_f32_e32 v124, v124
	v_rcp_f32_e32 v125, v125
	v_pk_mul_f32 v[68:69], v[68:69], v[146:147] op_sel_hi:[1,0]
	v_pk_mul_f32 v[62:63], v[62:63], v[140:141] op_sel_hi:[1,0]
	v_pk_mul_f32 v[58:59], v[58:59], v[140:141] op_sel_hi:[1,0]
	v_pk_mul_f32 v[118:119], v[118:119], v[124:125]
	v_pk_mul_f32 v[60:61], v[60:61], v[140:141] op_sel_hi:[1,0]
	v_pk_mul_f32 v[114:115], v[114:115], v[118:119]
	v_pk_mul_f32 v[118:119], v[120:121], v[200:201] op_sel_hi:[1,0]
	v_cvt_pk_bf16_f32 v124, v114, v115
	v_mul_f32_e32 v120, 0xbfb8aa3b, v118
	v_mul_f32_e32 v121, 0xbfb8aa3b, v119
	v_exp_f32_e32 v120, v120
	v_exp_f32_e32 v121, v121
	v_mov_b64_e32 v[114:115], s[68:69]
	v_pk_mul_f32 v[54:55], v[54:55], v[140:141] op_sel_hi:[1,0]
	v_add_f32_e32 v120, 1.0, v120
	v_add_f32_e32 v121, 1.0, v121
	v_rcp_f32_e32 v120, v120
	v_rcp_f32_e32 v121, v121
	v_pk_mul_f32 v[50:51], v[50:51], v[140:141] op_sel_hi:[1,0]
	v_pk_mul_f32 v[52:53], v[52:53], v[140:141] op_sel_hi:[1,0]
	v_pk_mul_f32 v[46:47], v[46:47], v[138:139] op_sel_hi:[1,0]
	v_pk_mul_f32 v[118:119], v[118:119], v[120:121]
	v_pk_mul_f32 v[42:43], v[42:43], v[138:139] op_sel_hi:[1,0]
	v_pk_mul_f32 v[116:117], v[116:117], v[118:119]
	v_mad_i64_i32 v[118:119], s[22:23], v196, s38, v[114:115]
	v_cvt_pk_bf16_f32 v125, v116, v117
	v_lshlrev_b64 v[116:117], 1, v[134:135]
	v_lshl_add_u64 v[118:119], v[118:119], 0, v[116:117]
	global_store_dwordx4 v[118:119], v[122:125], off
	v_mul_f32_e32 v118, 0xbfb8aa3b, v110
	v_mul_f32_e32 v119, 0xbfb8aa3b, v111
	v_exp_f32_e32 v118, v118
	v_exp_f32_e32 v119, v119
	v_pk_mul_f32 v[44:45], v[44:45], v[138:139] op_sel_hi:[1,0]
	v_pk_mul_f32 v[38:39], v[38:39], v[138:139] op_sel_hi:[1,0]
	v_add_f32_e32 v118, 1.0, v118
	v_add_f32_e32 v119, 1.0, v119
	v_rcp_f32_e32 v118, v118
	v_rcp_f32_e32 v119, v119
	v_pk_mul_f32 v[34:35], v[34:35], v[138:139] op_sel_hi:[1,0]
	v_pk_mul_f32 v[36:37], v[36:37], v[138:139] op_sel_hi:[1,0]
	v_pk_mul_f32 v[30:31], v[30:31], v[132:133] op_sel_hi:[1,0]
	v_pk_mul_f32 v[110:111], v[110:111], v[118:119]
	v_pk_mul_f32 v[26:27], v[26:27], v[132:133] op_sel_hi:[1,0]
	v_pk_mul_f32 v[106:107], v[106:107], v[110:111]
	v_pk_mul_f32 v[110:111], v[112:113], v[198:199] op_sel_hi:[1,0]
	v_cvt_pk_bf16_f32 v106, v106, v107
	v_mul_f32_e32 v112, 0xbfb8aa3b, v110
	v_mul_f32_e32 v113, 0xbfb8aa3b, v111
	v_exp_f32_e32 v112, v112
	v_exp_f32_e32 v113, v113
	v_pk_mul_f32 v[28:29], v[28:29], v[132:133] op_sel_hi:[1,0]
	v_pk_mul_f32 v[22:23], v[22:23], v[132:133] op_sel_hi:[1,0]
	v_add_f32_e32 v112, 1.0, v112
	v_add_f32_e32 v113, 1.0, v113
	v_rcp_f32_e32 v112, v112
	v_rcp_f32_e32 v113, v113
	v_pk_mul_f32 v[18:19], v[18:19], v[132:133] op_sel_hi:[1,0]
	v_pk_mul_f32 v[20:21], v[20:21], v[132:133] op_sel_hi:[1,0]
	v_pk_mul_f32 v[14:15], v[14:15], v[130:131] op_sel_hi:[1,0]
	v_pk_mul_f32 v[110:111], v[110:111], v[112:113]
	v_pk_mul_f32 v[10:11], v[10:11], v[130:131] op_sel_hi:[1,0]
	v_pk_mul_f32 v[108:109], v[108:109], v[110:111]
	v_pk_mul_f32 v[12:13], v[12:13], v[130:131] op_sel_hi:[1,0]
	v_cvt_pk_bf16_f32 v107, v108, v109
	v_mul_f32_e32 v108, 0xbfb8aa3b, v102
	v_mul_f32_e32 v109, 0xbfb8aa3b, v103
	v_exp_f32_e32 v108, v108
	v_exp_f32_e32 v109, v109
	v_pk_mul_f32 v[6:7], v[6:7], v[130:131] op_sel_hi:[1,0]
	v_pk_mul_f32 v[2:3], v[2:3], v[130:131] op_sel_hi:[1,0]
	v_add_f32_e32 v108, 1.0, v108
	v_add_f32_e32 v109, 1.0, v109
	v_rcp_f32_e32 v108, v108
	v_rcp_f32_e32 v109, v109
	v_pk_mul_f32 v[4:5], v[4:5], v[130:131] op_sel_hi:[1,0]
	s_and_b64 vcc, exec, s[40:41]
	s_mov_b32 s34, s6
	v_pk_mul_f32 v[102:103], v[102:103], v[108:109]
	s_nop 0
	v_pk_mul_f32 v[98:99], v[98:99], v[102:103]
	v_pk_mul_f32 v[102:103], v[104:105], v[198:199] op_sel_hi:[1,0]
	v_cvt_pk_bf16_f32 v108, v98, v99
	v_mul_f32_e32 v104, 0xbfb8aa3b, v102
	v_mul_f32_e32 v105, 0xbfb8aa3b, v103
	v_exp_f32_e32 v104, v104
	v_exp_f32_e32 v105, v105
	v_mad_i64_i32 v[98:99], s[22:23], v194, s38, v[114:115]
	v_add_f32_e32 v104, 1.0, v104
	v_add_f32_e32 v105, 1.0, v105
	v_rcp_f32_e32 v104, v104
	v_rcp_f32_e32 v105, v105
	v_lshl_add_u64 v[98:99], v[98:99], 0, v[116:117]
	v_pk_mul_f32 v[102:103], v[102:103], v[104:105]
	s_nop 0
	v_pk_mul_f32 v[100:101], v[100:101], v[102:103]
	s_nop 0
	v_cvt_pk_bf16_f32 v109, v100, v101
	global_store_dwordx4 v[98:99], v[106:109], off
	v_mul_f32_e32 v98, 0xbfb8aa3b, v94
	v_mul_f32_e32 v99, 0xbfb8aa3b, v95
	v_exp_f32_e32 v98, v98
	v_exp_f32_e32 v99, v99
	v_add_f32_e32 v98, 1.0, v98
	v_add_f32_e32 v99, 1.0, v99
	v_rcp_f32_e32 v98, v98
	v_rcp_f32_e32 v99, v99
	s_nop 0
	v_pk_mul_f32 v[94:95], v[94:95], v[98:99]
	s_nop 0
	v_pk_mul_f32 v[90:91], v[90:91], v[94:95]
	v_pk_mul_f32 v[94:95], v[96:97], v[148:149] op_sel_hi:[1,0]
	v_cvt_pk_bf16_f32 v90, v90, v91
	v_mul_f32_e32 v96, 0xbfb8aa3b, v94
	v_mul_f32_e32 v97, 0xbfb8aa3b, v95
	v_exp_f32_e32 v96, v96
	v_exp_f32_e32 v97, v97
	v_add_f32_e32 v96, 1.0, v96
	v_add_f32_e32 v97, 1.0, v97
	v_rcp_f32_e32 v96, v96
	v_rcp_f32_e32 v97, v97
	s_nop 0
	v_pk_mul_f32 v[94:95], v[94:95], v[96:97]
	s_nop 0
	v_pk_mul_f32 v[92:93], v[92:93], v[94:95]
	s_nop 0
	v_cvt_pk_bf16_f32 v91, v92, v93
	v_mul_f32_e32 v92, 0xbfb8aa3b, v86
	v_mul_f32_e32 v93, 0xbfb8aa3b, v87
	v_exp_f32_e32 v92, v92
	v_exp_f32_e32 v93, v93
	v_add_f32_e32 v92, 1.0, v92
	v_add_f32_e32 v93, 1.0, v93
	v_rcp_f32_e32 v92, v92
	v_rcp_f32_e32 v93, v93
	s_nop 0
	v_pk_mul_f32 v[86:87], v[86:87], v[92:93]
	s_nop 0
	v_pk_mul_f32 v[82:83], v[82:83], v[86:87]
	v_pk_mul_f32 v[86:87], v[88:89], v[148:149] op_sel_hi:[1,0]
	v_cvt_pk_bf16_f32 v92, v82, v83
	v_mul_f32_e32 v88, 0xbfb8aa3b, v86
	v_mul_f32_e32 v89, 0xbfb8aa3b, v87
	v_exp_f32_e32 v88, v88
	v_exp_f32_e32 v89, v89
	v_mad_i64_i32 v[82:83], s[22:23], v192, s38, v[114:115]
	v_add_f32_e32 v88, 1.0, v88
	v_add_f32_e32 v89, 1.0, v89
	v_rcp_f32_e32 v88, v88
	v_rcp_f32_e32 v89, v89
	v_lshl_add_u64 v[82:83], v[82:83], 0, v[116:117]
	v_pk_mul_f32 v[86:87], v[86:87], v[88:89]
	s_nop 0
	v_pk_mul_f32 v[84:85], v[84:85], v[86:87]
	s_nop 0
	v_cvt_pk_bf16_f32 v93, v84, v85
	global_store_dwordx4 v[82:83], v[90:93], off
	v_mul_f32_e32 v82, 0xbfb8aa3b, v78
	v_mul_f32_e32 v83, 0xbfb8aa3b, v79
	v_exp_f32_e32 v82, v82
	v_exp_f32_e32 v83, v83
	v_add_f32_e32 v82, 1.0, v82
	v_add_f32_e32 v83, 1.0, v83
	v_rcp_f32_e32 v82, v82
	v_rcp_f32_e32 v83, v83
	s_nop 0
	v_pk_mul_f32 v[78:79], v[78:79], v[82:83]
	s_nop 0
	v_pk_mul_f32 v[74:75], v[74:75], v[78:79]
	v_pk_mul_f32 v[78:79], v[80:81], v[146:147] op_sel_hi:[1,0]
	v_cvt_pk_bf16_f32 v74, v74, v75
	v_mul_f32_e32 v80, 0xbfb8aa3b, v78
	v_mul_f32_e32 v81, 0xbfb8aa3b, v79
	v_exp_f32_e32 v80, v80
	v_exp_f32_e32 v81, v81
	v_add_f32_e32 v80, 1.0, v80
	v_add_f32_e32 v81, 1.0, v81
	v_rcp_f32_e32 v80, v80
	v_rcp_f32_e32 v81, v81
	s_nop 0
	v_pk_mul_f32 v[78:79], v[78:79], v[80:81]
	s_nop 0
	v_pk_mul_f32 v[76:77], v[76:77], v[78:79]
	s_nop 0
	v_cvt_pk_bf16_f32 v75, v76, v77
	v_mul_f32_e32 v76, 0xbfb8aa3b, v70
	v_mul_f32_e32 v77, 0xbfb8aa3b, v71
	v_exp_f32_e32 v76, v76
	v_exp_f32_e32 v77, v77
	v_add_f32_e32 v76, 1.0, v76
	v_add_f32_e32 v77, 1.0, v77
	v_rcp_f32_e32 v76, v76
	v_rcp_f32_e32 v77, v77
	s_nop 0
	v_pk_mul_f32 v[70:71], v[70:71], v[76:77]
	s_nop 0
	v_pk_mul_f32 v[66:67], v[66:67], v[70:71]
	v_pk_mul_f32 v[70:71], v[72:73], v[146:147] op_sel_hi:[1,0]
	v_cvt_pk_bf16_f32 v76, v66, v67
	v_mul_f32_e32 v72, 0xbfb8aa3b, v70
	v_mul_f32_e32 v73, 0xbfb8aa3b, v71
	v_exp_f32_e32 v72, v72
	v_exp_f32_e32 v73, v73
	v_mad_i64_i32 v[66:67], s[22:23], v190, s38, v[114:115]
	v_add_f32_e32 v72, 1.0, v72
	v_add_f32_e32 v73, 1.0, v73
	v_rcp_f32_e32 v72, v72
	v_rcp_f32_e32 v73, v73
	v_lshl_add_u64 v[66:67], v[66:67], 0, v[116:117]
	v_pk_mul_f32 v[70:71], v[70:71], v[72:73]
	s_nop 0
	v_pk_mul_f32 v[68:69], v[68:69], v[70:71]
	s_nop 0
	v_cvt_pk_bf16_f32 v77, v68, v69
	global_store_dwordx4 v[66:67], v[74:77], off
	v_mul_f32_e32 v66, 0xbfb8aa3b, v62
	v_mul_f32_e32 v67, 0xbfb8aa3b, v63
	v_exp_f32_e32 v66, v66
	v_exp_f32_e32 v67, v67
	v_add_f32_e32 v66, 1.0, v66
	v_add_f32_e32 v67, 1.0, v67
	v_rcp_f32_e32 v66, v66
	v_rcp_f32_e32 v67, v67
	s_nop 0
	v_pk_mul_f32 v[62:63], v[62:63], v[66:67]
	s_nop 0
	v_pk_mul_f32 v[58:59], v[58:59], v[62:63]
	v_pk_mul_f32 v[62:63], v[64:65], v[140:141] op_sel_hi:[1,0]
	v_cvt_pk_bf16_f32 v58, v58, v59
	v_mul_f32_e32 v64, 0xbfb8aa3b, v62
	v_mul_f32_e32 v65, 0xbfb8aa3b, v63
	v_exp_f32_e32 v64, v64
	v_exp_f32_e32 v65, v65
	v_add_f32_e32 v64, 1.0, v64
	v_add_f32_e32 v65, 1.0, v65
	v_rcp_f32_e32 v64, v64
	v_rcp_f32_e32 v65, v65
	s_nop 0
	v_pk_mul_f32 v[62:63], v[62:63], v[64:65]
	s_nop 0
	v_pk_mul_f32 v[60:61], v[60:61], v[62:63]
	s_nop 0
	v_cvt_pk_bf16_f32 v59, v60, v61
	v_mul_f32_e32 v60, 0xbfb8aa3b, v54
	v_mul_f32_e32 v61, 0xbfb8aa3b, v55
	v_exp_f32_e32 v60, v60
	v_exp_f32_e32 v61, v61
	v_add_f32_e32 v60, 1.0, v60
	v_add_f32_e32 v61, 1.0, v61
	v_rcp_f32_e32 v60, v60
	v_rcp_f32_e32 v61, v61
	s_nop 0
	v_pk_mul_f32 v[54:55], v[54:55], v[60:61]
	s_nop 0
	v_pk_mul_f32 v[50:51], v[50:51], v[54:55]
	v_pk_mul_f32 v[54:55], v[56:57], v[140:141] op_sel_hi:[1,0]
	v_cvt_pk_bf16_f32 v60, v50, v51
	v_mul_f32_e32 v56, 0xbfb8aa3b, v54
	v_mul_f32_e32 v57, 0xbfb8aa3b, v55
	v_exp_f32_e32 v56, v56
	v_exp_f32_e32 v57, v57
	v_mad_i64_i32 v[50:51], s[22:23], v188, s38, v[114:115]
	v_add_f32_e32 v56, 1.0, v56
	v_add_f32_e32 v57, 1.0, v57
	v_rcp_f32_e32 v56, v56
	v_rcp_f32_e32 v57, v57
	v_lshl_add_u64 v[50:51], v[50:51], 0, v[116:117]
	v_pk_mul_f32 v[54:55], v[54:55], v[56:57]
	s_nop 0
	v_pk_mul_f32 v[52:53], v[52:53], v[54:55]
	s_nop 0
	v_cvt_pk_bf16_f32 v61, v52, v53
	global_store_dwordx4 v[50:51], v[58:61], off
	v_mul_f32_e32 v50, 0xbfb8aa3b, v46
	v_mul_f32_e32 v51, 0xbfb8aa3b, v47
	v_exp_f32_e32 v50, v50
	v_exp_f32_e32 v51, v51
	v_add_f32_e32 v50, 1.0, v50
	v_add_f32_e32 v51, 1.0, v51
	v_rcp_f32_e32 v50, v50
	v_rcp_f32_e32 v51, v51
	s_nop 0
	v_pk_mul_f32 v[46:47], v[46:47], v[50:51]
	s_nop 0
	v_pk_mul_f32 v[42:43], v[42:43], v[46:47]
	v_pk_mul_f32 v[46:47], v[48:49], v[138:139] op_sel_hi:[1,0]
	v_cvt_pk_bf16_f32 v42, v42, v43
	v_mul_f32_e32 v48, 0xbfb8aa3b, v46
	v_mul_f32_e32 v49, 0xbfb8aa3b, v47
	v_exp_f32_e32 v48, v48
	v_exp_f32_e32 v49, v49
	v_add_f32_e32 v48, 1.0, v48
	v_add_f32_e32 v49, 1.0, v49
	v_rcp_f32_e32 v48, v48
	v_rcp_f32_e32 v49, v49
	s_nop 0
	v_pk_mul_f32 v[46:47], v[46:47], v[48:49]
	s_nop 0
	v_pk_mul_f32 v[44:45], v[44:45], v[46:47]
	s_nop 0
	v_cvt_pk_bf16_f32 v43, v44, v45
	v_mul_f32_e32 v44, 0xbfb8aa3b, v38
	v_mul_f32_e32 v45, 0xbfb8aa3b, v39
	v_exp_f32_e32 v44, v44
	v_exp_f32_e32 v45, v45
	v_add_f32_e32 v44, 1.0, v44
	v_add_f32_e32 v45, 1.0, v45
	v_rcp_f32_e32 v44, v44
	v_rcp_f32_e32 v45, v45
	s_nop 0
	v_pk_mul_f32 v[38:39], v[38:39], v[44:45]
	s_nop 0
	v_pk_mul_f32 v[34:35], v[34:35], v[38:39]
	v_pk_mul_f32 v[38:39], v[40:41], v[138:139] op_sel_hi:[1,0]
	v_cvt_pk_bf16_f32 v44, v34, v35
	v_mul_f32_e32 v40, 0xbfb8aa3b, v38
	v_mul_f32_e32 v41, 0xbfb8aa3b, v39
	v_exp_f32_e32 v40, v40
	v_exp_f32_e32 v41, v41
	v_mad_i64_i32 v[34:35], s[22:23], v186, s38, v[114:115]
	v_add_f32_e32 v40, 1.0, v40
	v_add_f32_e32 v41, 1.0, v41
	v_rcp_f32_e32 v40, v40
	v_rcp_f32_e32 v41, v41
	v_lshl_add_u64 v[34:35], v[34:35], 0, v[116:117]
	v_pk_mul_f32 v[38:39], v[38:39], v[40:41]
	s_nop 0
	v_pk_mul_f32 v[36:37], v[36:37], v[38:39]
	s_nop 0
	v_cvt_pk_bf16_f32 v45, v36, v37
	global_store_dwordx4 v[34:35], v[42:45], off
	v_mul_f32_e32 v34, 0xbfb8aa3b, v30
	v_mul_f32_e32 v35, 0xbfb8aa3b, v31
	v_exp_f32_e32 v34, v34
	v_exp_f32_e32 v35, v35
	v_add_f32_e32 v34, 1.0, v34
	v_add_f32_e32 v35, 1.0, v35
	v_rcp_f32_e32 v34, v34
	v_rcp_f32_e32 v35, v35
	s_nop 0
	v_pk_mul_f32 v[30:31], v[30:31], v[34:35]
	s_nop 0
	v_pk_mul_f32 v[26:27], v[26:27], v[30:31]
	v_pk_mul_f32 v[30:31], v[32:33], v[132:133] op_sel_hi:[1,0]
	v_cvt_pk_bf16_f32 v26, v26, v27
	v_mul_f32_e32 v32, 0xbfb8aa3b, v30
	v_mul_f32_e32 v33, 0xbfb8aa3b, v31
	v_exp_f32_e32 v32, v32
	v_exp_f32_e32 v33, v33
	v_add_f32_e32 v32, 1.0, v32
	v_add_f32_e32 v33, 1.0, v33
	v_rcp_f32_e32 v32, v32
	v_rcp_f32_e32 v33, v33
	s_nop 0
	v_pk_mul_f32 v[30:31], v[30:31], v[32:33]
	s_nop 0
	v_pk_mul_f32 v[28:29], v[28:29], v[30:31]
	s_nop 0
	v_cvt_pk_bf16_f32 v27, v28, v29
	v_mul_f32_e32 v28, 0xbfb8aa3b, v22
	v_mul_f32_e32 v29, 0xbfb8aa3b, v23
	v_exp_f32_e32 v28, v28
	v_exp_f32_e32 v29, v29
	v_add_f32_e32 v28, 1.0, v28
	v_add_f32_e32 v29, 1.0, v29
	v_rcp_f32_e32 v28, v28
	v_rcp_f32_e32 v29, v29
	s_nop 0
	v_pk_mul_f32 v[22:23], v[22:23], v[28:29]
	s_nop 0
	v_pk_mul_f32 v[18:19], v[18:19], v[22:23]
	v_pk_mul_f32 v[22:23], v[24:25], v[132:133] op_sel_hi:[1,0]
	v_cvt_pk_bf16_f32 v28, v18, v19
	v_mul_f32_e32 v24, 0xbfb8aa3b, v22
	v_mul_f32_e32 v25, 0xbfb8aa3b, v23
	v_exp_f32_e32 v24, v24
	v_exp_f32_e32 v25, v25
	v_mad_i64_i32 v[18:19], s[22:23], v184, s38, v[114:115]
	v_add_f32_e32 v24, 1.0, v24
	v_add_f32_e32 v25, 1.0, v25
	v_rcp_f32_e32 v24, v24
	v_rcp_f32_e32 v25, v25
	v_lshl_add_u64 v[18:19], v[18:19], 0, v[116:117]
	v_pk_mul_f32 v[22:23], v[22:23], v[24:25]
	s_nop 0
	v_pk_mul_f32 v[20:21], v[20:21], v[22:23]
	s_nop 0
	v_cvt_pk_bf16_f32 v29, v20, v21
	global_store_dwordx4 v[18:19], v[26:29], off
	v_mul_f32_e32 v18, 0xbfb8aa3b, v14
	v_mul_f32_e32 v19, 0xbfb8aa3b, v15
	v_exp_f32_e32 v18, v18
	v_exp_f32_e32 v19, v19
	v_add_f32_e32 v18, 1.0, v18
	v_add_f32_e32 v19, 1.0, v19
	v_rcp_f32_e32 v18, v18
	v_rcp_f32_e32 v19, v19
	s_nop 0
	v_pk_mul_f32 v[14:15], v[14:15], v[18:19]
	s_nop 0
	v_pk_mul_f32 v[10:11], v[10:11], v[14:15]
	v_pk_mul_f32 v[14:15], v[16:17], v[130:131] op_sel_hi:[1,0]
	v_cvt_pk_bf16_f32 v10, v10, v11
	v_mul_f32_e32 v16, 0xbfb8aa3b, v14
	v_mul_f32_e32 v17, 0xbfb8aa3b, v15
	v_exp_f32_e32 v16, v16
	v_exp_f32_e32 v17, v17
	v_add_f32_e32 v16, 1.0, v16
	v_add_f32_e32 v17, 1.0, v17
	v_rcp_f32_e32 v16, v16
	v_rcp_f32_e32 v17, v17
	s_nop 0
	v_pk_mul_f32 v[14:15], v[14:15], v[16:17]
	s_nop 0
	v_pk_mul_f32 v[12:13], v[12:13], v[14:15]
	s_nop 0
	v_cvt_pk_bf16_f32 v11, v12, v13
	v_mul_f32_e32 v12, 0xbfb8aa3b, v6
	v_mul_f32_e32 v13, 0xbfb8aa3b, v7
	v_exp_f32_e32 v12, v12
	v_exp_f32_e32 v13, v13
	v_add_f32_e32 v12, 1.0, v12
	v_add_f32_e32 v13, 1.0, v13
	v_rcp_f32_e32 v12, v12
	v_rcp_f32_e32 v13, v13
	s_nop 0
	v_pk_mul_f32 v[6:7], v[6:7], v[12:13]
	s_nop 0
	v_pk_mul_f32 v[2:3], v[2:3], v[6:7]
	v_pk_mul_f32 v[6:7], v[8:9], v[130:131] op_sel_hi:[1,0]
	v_cvt_pk_bf16_f32 v12, v2, v3
	v_mul_f32_e32 v8, 0xbfb8aa3b, v6
	v_mul_f32_e32 v9, 0xbfb8aa3b, v7
	v_exp_f32_e32 v8, v8
	v_exp_f32_e32 v9, v9
	v_mad_i64_i32 v[2:3], s[22:23], v182, s38, v[114:115]
	v_add_f32_e32 v8, 1.0, v8
	v_add_f32_e32 v9, 1.0, v9
	v_rcp_f32_e32 v8, v8
	v_rcp_f32_e32 v9, v9
	v_lshl_add_u64 v[2:3], v[2:3], 0, v[116:117]
	v_pk_mul_f32 v[6:7], v[6:7], v[8:9]
	s_nop 0
	v_pk_mul_f32 v[4:5], v[4:5], v[6:7]
	s_nop 0
	v_cvt_pk_bf16_f32 v13, v4, v5
	global_store_dwordx4 v[2:3], v[10:13], off
	s_cbranch_vccz .LBB0_80
	s_waitcnt vmcnt(0)
	s_cmpk_gt_u32 s0, 0xff
	s_cbranch_scc1 .LBB0_87
	s_barrier

.LBB0_284:
	s_and_b32 s1, s7, 3
	s_add_i32 m0, s16, 0x18000
	v_lshl_add_u64 v[8:9], v[8:9], 0, s[12:13]
	s_lshl_b32 s7, s6, 13
	s_lshl_b32 s24, s1, 12
	s_waitcnt vmcnt(2)
	s_barrier
	global_load_lds_dwordx4 v[8:9], off
	v_lshl_add_u64 v[6:7], v[6:7], 0, s[12:13]
	s_add_i32 m0, s16, 0x1a000
	s_add_i32 s34, s16, 0x8000
	s_add_i32 s46, s16, 0xa000
	global_load_lds_dwordx4 v[6:7], off
	v_lshl_add_u64 v[4:5], v[4:5], 0, s[12:13]
	s_mov_b32 m0, s34
	s_add_u32 s22, s30, 0x40080
	global_load_lds_dwordx4 v[4:5], off
	v_lshl_add_u64 v[2:3], v[2:3], 0, s[12:13]
	s_mov_b32 m0, s46
	s_addc_u32 s23, s31, 0
	global_load_lds_dwordx4 v[2:3], off
	s_add_i32 m0, s16, 0x1c000
	v_lshl_add_u64 v[2:3], s[22:23], 0, v[0:1]
	global_load_lds_dwordx4 v[2:3], off
	v_lshl_add_u64 v[2:3], s[22:23], 0, v[178:179]
	s_add_i32 m0, s16, 0x1e000
	v_bfe_u32 v4, v13, 4, 2
	global_load_lds_dwordx4 v[2:3], off
	v_and_b32_e32 v3, 15, v13
	v_lshlrev_b32_e32 v2, 4, v4
	v_lshlrev_b32_e32 v6, 2, v13
	v_lshl_or_b32 v216, s6, 6, v3
	v_lshl_or_b32 v3, v3, 6, v2
	v_and_b32_e32 v6, 32, v6
	v_lshlrev_b32_e32 v5, 3, v4
	v_bitop3_b32 v7, v3, s7, v6 bitop3:0xde
	v_readlane_b32 s6, v254, 50
	v_lshl_or_b32 v218, s1, 5, v5
	v_lshlrev_b32_e32 v4, 5, v4
	v_mov_b32_e32 v5, v1
	v_readlane_b32 s7, v254, 51
	v_bitop3_b32 v217, v3, s24, v6 bitop3:0xde
	v_mov_b32_e32 v3, v1
	v_lshl_add_u64 v[184:185], s[6:7], 0, v[4:5]
	v_readlane_b32 s6, v254, 37
	v_readlane_b32 s7, v254, 38
	s_waitcnt vmcnt(6)
	s_barrier
	s_cmp_eq_u32 s1, 0
	v_lshl_add_u64 v[186:187], s[6:7], 0, v[2:3]
	v_readlane_b32 s6, v254, 31
	v_lshlrev_b32_e32 v2, 14, v15
	v_readlane_b32 s7, v254, 32
	v_and_b32_e32 v2, 0xffff8000, v2
	s_load_dwordx2 s[6:7], s[6:7], 0x28
	v_lshl_add_u32 v2, v14, 11, v2
	v_and_b32_e32 v3, 1, v15
	v_lshl_or_b32 v2, v3, 6, v2
	v_lshl_add_u32 v190, v16, 1, v2
	v_lshlrev_b32_e32 v2, 14, v10
	v_and_b32_e32 v2, 0xffff8000, v2
	v_lshl_add_u32 v2, v11, 11, v2
	v_and_b32_e32 v3, 1, v10
	s_waitcnt lgkmcnt(0)
	v_lshl_add_u64 v[188:189], s[6:7], 0, v[4:5]
	v_lshl_or_b32 v2, v3, 6, v2
	v_readlane_b32 s6, v253, 17
	s_mov_b32 s47, 0
	s_cselect_b64 s[24:25], -1, 0
	v_mov_b32_e32 v191, v1
	v_lshl_add_u32 v192, v12, 1, v2
	v_mov_b32_e32 v193, v1
	v_add_u32_e32 v219, 0, v7
	v_readlane_b32 s48, v253, 14
	s_mov_b32 s49, s6
	v_readlane_b32 s7, v253, 18
	s_branch .LBB0_286

.LBB0_289:
	s_add_u32 s1, s42, 0xfffc0080
	s_addc_u32 s22, s43, -1
	s_add_i32 s23, 0, 0x10000
	v_add_u32_e32 v142, s23, v217
	ds_read_b128 v[130:133], v142
	ds_read_b128 v[134:137], v142 offset:1024
	ds_read_b128 v[138:141], v142 offset:2048
	ds_read_b128 v[142:145], v142 offset:3072
	s_cmp_eq_u32 s54, 12
	s_cselect_b32 s45, s27, s22
	s_cselect_b32 s44, s50, s1
	s_cselect_b32 s31, s7, s53
	s_cselect_b32 s30, s51, s52
	v_lshl_add_u64 v[176:177], s[42:43], 0, v[190:191]
	s_add_i32 m0, s16, 0xc000
	ds_read_b128 v[146:149], v219
	ds_read_b128 v[150:153], v219 offset:1024
	ds_read_b128 v[154:157], v219 offset:2048
	ds_read_b128 v[158:161], v219 offset:3072
	ds_read_b128 v[194:197], v219 offset:4096
	ds_read_b128 v[198:201], v219 offset:5120
	ds_read_b128 v[202:205], v219 offset:6144
	ds_read_b128 v[206:209], v219 offset:7168
	global_load_lds_dwordx4 v[176:177], off
	v_lshl_add_u64 v[176:177], s[42:43], 0, v[192:193]
	s_add_i32 m0, s16, 0xe000
	s_nop 0
	global_load_lds_dwordx4 v[176:177], off
	s_add_i32 s1, 0, 0x14000
	v_add_u32_e32 v168, s1, v217
	ds_read_b128 v[230:233], v168
	ds_read_b128 v[234:237], v168 offset:1024
	ds_read_b128 v[238:241], v168 offset:2048
	ds_read_b128 v[242:245], v168 offset:3072
	s_waitcnt vmcnt(8)
	s_waitcnt lgkmcnt(0)
	s_barrier
	s_setprio 1
	v_mfma_f32_16x16x32_bf16 v[126:129], v[130:133], v[146:149], v[126:129]
	v_mfma_f32_16x16x32_bf16 v[122:125], v[138:141], v[146:149], v[122:125]
	v_mfma_f32_16x16x32_bf16 v[118:121], v[130:133], v[154:157], v[118:121]
	v_mfma_f32_16x16x32_bf16 v[110:113], v[138:141], v[154:157], v[110:113]
	v_mfma_f32_16x16x32_bf16 v[102:105], v[130:133], v[194:197], v[102:105]
	v_mfma_f32_16x16x32_bf16 v[94:97], v[138:141], v[194:197], v[94:97]
	v_mfma_f32_16x16x32_bf16 v[86:89], v[130:133], v[202:205], v[86:89]
	v_mfma_f32_16x16x32_bf16 v[78:81], v[138:141], v[202:205], v[78:81]
	v_mfma_f32_16x16x32_bf16 v[126:129], v[134:137], v[150:153], v[126:129]
	v_mfma_f32_16x16x32_bf16 v[122:125], v[142:145], v[150:153], v[122:125]
	v_mfma_f32_16x16x32_bf16 v[118:121], v[134:137], v[158:161], v[118:121]
	v_mfma_f32_16x16x32_bf16 v[110:113], v[142:145], v[158:161], v[110:113]
	v_mfma_f32_16x16x32_bf16 v[102:105], v[134:137], v[198:201], v[102:105]
	v_mfma_f32_16x16x32_bf16 v[94:97], v[142:145], v[198:201], v[94:97]
	v_mfma_f32_16x16x32_bf16 v[86:89], v[134:137], v[206:209], v[86:89]
	v_mfma_f32_16x16x32_bf16 v[78:81], v[142:145], v[206:209], v[78:81]
	v_mfma_f32_16x16x32_bf16 v[114:117], v[230:233], v[146:149], v[114:117]
	v_mfma_f32_16x16x32_bf16 v[106:109], v[238:241], v[146:149], v[106:109]
	v_mfma_f32_16x16x32_bf16 v[98:101], v[230:233], v[154:157], v[98:101]
	v_mfma_f32_16x16x32_bf16 v[90:93], v[238:241], v[154:157], v[90:93]
	v_mfma_f32_16x16x32_bf16 v[82:85], v[230:233], v[194:197], v[82:85]
	v_mfma_f32_16x16x32_bf16 v[74:77], v[238:241], v[194:197], v[74:77]
	v_mfma_f32_16x16x32_bf16 v[70:73], v[230:233], v[202:205], v[70:73]
	v_mfma_f32_16x16x32_bf16 v[66:69], v[238:241], v[202:205], v[66:69]
	v_mfma_f32_16x16x32_bf16 v[114:117], v[234:237], v[150:153], v[114:117]
	v_mfma_f32_16x16x32_bf16 v[106:109], v[242:245], v[150:153], v[106:109]
	v_mfma_f32_16x16x32_bf16 v[98:101], v[234:237], v[158:161], v[98:101]
	v_mfma_f32_16x16x32_bf16 v[90:93], v[242:245], v[158:161], v[90:93]
	v_mfma_f32_16x16x32_bf16 v[82:85], v[234:237], v[198:201], v[82:85]
	v_mfma_f32_16x16x32_bf16 v[74:77], v[242:245], v[198:201], v[74:77]
	v_mfma_f32_16x16x32_bf16 v[70:73], v[234:237], v[206:209], v[70:73]
	v_mfma_f32_16x16x32_bf16 v[66:69], v[242:245], v[206:209], v[66:69]
	s_setprio 0
	s_barrier
	ds_read_b128 v[146:149], v219 offset:16384
	ds_read_b128 v[150:153], v219 offset:17408
	ds_read_b128 v[154:157], v219 offset:18432
	ds_read_b128 v[158:161], v219 offset:19456
	ds_read_b128 v[194:197], v219 offset:20480
	ds_read_b128 v[198:201], v219 offset:21504
	ds_read_b128 v[202:205], v219 offset:22528
	ds_read_b128 v[206:209], v219 offset:23552
	s_add_i32 s22, s23, s4
	v_lshl_add_u64 v[176:177], s[30:31], 0, v[0:1]
	s_mov_b32 m0, s22
	s_nop 0
	global_load_lds_dwordx4 v[176:177], off
	v_lshl_add_u64 v[220:221], s[30:31], 0, v[178:179]
	s_add_i32 m0, s22, 0x2000
	s_nop 0
	global_load_lds_dwordx4 v[220:221], off
	s_mov_b32 m0, s16
	v_lshl_add_u64 v[246:247], s[44:45], 0, v[182:183]
	global_load_lds_dwordx4 v[246:247], off
	v_lshl_add_u64 v[248:249], s[44:45], 0, v[180:181]
	s_mov_b32 m0, s17
	s_nop 0
	global_load_lds_dwordx4 v[248:249], off
	s_add_u32 s22, s30, 0x40000
	s_addc_u32 s23, s31, 0
	s_add_i32 s1, s1, s4
	s_mov_b32 m0, s1
	s_nop 0
	global_load_lds_dwordx4 v0, s[22:23]
	s_add_i32 m0, s1, 0x2000
	s_nop 0
	global_load_lds_dwordx4 v178, s[22:23]
	s_waitcnt vmcnt(8)
	s_waitcnt lgkmcnt(0)
	s_barrier
	s_setprio 1
	v_mfma_f32_16x16x32_bf16 v[62:65], v[130:133], v[146:149], v[62:65]
	v_mfma_f32_16x16x32_bf16 v[58:61], v[138:141], v[146:149], v[58:61]
	v_mfma_f32_16x16x32_bf16 v[54:57], v[130:133], v[154:157], v[54:57]
	v_mfma_f32_16x16x32_bf16 v[46:49], v[138:141], v[154:157], v[46:49]
	v_mfma_f32_16x16x32_bf16 v[38:41], v[130:133], v[194:197], v[38:41]
	v_mfma_f32_16x16x32_bf16 v[30:33], v[138:141], v[194:197], v[30:33]
	v_mfma_f32_16x16x32_bf16 v[22:25], v[130:133], v[202:205], v[22:25]
	v_mfma_f32_16x16x32_bf16 v[14:17], v[138:141], v[202:205], v[14:17]
	v_mfma_f32_16x16x32_bf16 v[62:65], v[134:137], v[150:153], v[62:65]
	v_mfma_f32_16x16x32_bf16 v[58:61], v[142:145], v[150:153], v[58:61]
	v_mfma_f32_16x16x32_bf16 v[54:57], v[134:137], v[158:161], v[54:57]
	v_mfma_f32_16x16x32_bf16 v[46:49], v[142:145], v[158:161], v[46:49]
	v_mfma_f32_16x16x32_bf16 v[38:41], v[134:137], v[198:201], v[38:41]
	v_mfma_f32_16x16x32_bf16 v[30:33], v[142:145], v[198:201], v[30:33]
	v_mfma_f32_16x16x32_bf16 v[22:25], v[134:137], v[206:209], v[22:25]
	v_mfma_f32_16x16x32_bf16 v[14:17], v[142:145], v[206:209], v[14:17]
	v_mfma_f32_16x16x32_bf16 v[50:53], v[230:233], v[146:149], v[50:53]
	v_mfma_f32_16x16x32_bf16 v[42:45], v[238:241], v[146:149], v[42:45]
	v_mfma_f32_16x16x32_bf16 v[34:37], v[230:233], v[154:157], v[34:37]
	v_mfma_f32_16x16x32_bf16 v[26:29], v[238:241], v[154:157], v[26:29]
	v_mfma_f32_16x16x32_bf16 v[18:21], v[230:233], v[194:197], v[18:21]
	v_mfma_f32_16x16x32_bf16 v[10:13], v[238:241], v[194:197], v[10:13]
	v_mfma_f32_16x16x32_bf16 v[6:9], v[230:233], v[202:205], v[6:9]
	v_mfma_f32_16x16x32_bf16 v[2:5], v[238:241], v[202:205], v[2:5]
	v_mfma_f32_16x16x32_bf16 v[50:53], v[234:237], v[150:153], v[50:53]
	v_mfma_f32_16x16x32_bf16 v[42:45], v[242:245], v[150:153], v[42:45]
	v_mfma_f32_16x16x32_bf16 v[34:37], v[234:237], v[158:161], v[34:37]
	v_mfma_f32_16x16x32_bf16 v[26:29], v[242:245], v[158:161], v[26:29]
	v_mfma_f32_16x16x32_bf16 v[18:21], v[234:237], v[198:201], v[18:21]
	v_mfma_f32_16x16x32_bf16 v[10:13], v[242:245], v[198:201], v[10:13]
	v_mfma_f32_16x16x32_bf16 v[6:9], v[234:237], v[206:209], v[6:9]
	v_mfma_f32_16x16x32_bf16 v[2:5], v[242:245], v[206:209], v[2:5]
	s_setprio 0
	s_barrier
	s_add_i32 s1, 0, 0x18000
	v_add_u32_e32 v142, s1, v217
	ds_read_b128 v[130:133], v142
	ds_read_b128 v[134:137], v142 offset:1024
	ds_read_b128 v[138:141], v142 offset:2048
	ds_read_b128 v[142:145], v142 offset:3072
	s_add_u32 s22, s44, 0x40000
	s_addc_u32 s23, s45, 0
	s_mov_b32 m0, s20
	v_lshl_add_u64 v[230:231], s[22:23], 0, v[182:183]
	ds_read_b128 v[146:149], v219 offset:32768
	ds_read_b128 v[150:153], v219 offset:33792
	ds_read_b128 v[154:157], v219 offset:34816
	ds_read_b128 v[158:161], v219 offset:35840
	ds_read_b128 v[194:197], v219 offset:36864
	ds_read_b128 v[198:201], v219 offset:37888
	ds_read_b128 v[202:205], v219 offset:38912
	ds_read_b128 v[206:209], v219 offset:39936
	global_load_lds_dwordx4 v[230:231], off
	v_lshl_add_u64 v[230:231], s[22:23], 0, v[180:181]
	s_mov_b32 m0, s21
	s_nop 0
	global_load_lds_dwordx4 v[230:231], off
	s_add_i32 s33, 0, 0x1c000
	v_add_u32_e32 v168, s33, v217
	ds_read_b128 v[230:233], v168
	ds_read_b128 v[234:237], v168 offset:1024
	ds_read_b128 v[238:241], v168 offset:2048
	ds_read_b128 v[242:245], v168 offset:3072
	s_waitcnt vmcnt(8)
	s_waitcnt lgkmcnt(0)
	s_barrier
	s_setprio 1
	v_mfma_f32_16x16x32_bf16 v[126:129], v[130:133], v[146:149], v[126:129]
	v_mfma_f32_16x16x32_bf16 v[122:125], v[138:141], v[146:149], v[122:125]
	v_mfma_f32_16x16x32_bf16 v[118:121], v[130:133], v[154:157], v[118:121]
	v_mfma_f32_16x16x32_bf16 v[110:113], v[138:141], v[154:157], v[110:113]
	v_mfma_f32_16x16x32_bf16 v[102:105], v[130:133], v[194:197], v[102:105]
	v_mfma_f32_16x16x32_bf16 v[94:97], v[138:141], v[194:197], v[94:97]
	v_mfma_f32_16x16x32_bf16 v[86:89], v[130:133], v[202:205], v[86:89]
	v_mfma_f32_16x16x32_bf16 v[78:81], v[138:141], v[202:205], v[78:81]
	v_mfma_f32_16x16x32_bf16 v[126:129], v[134:137], v[150:153], v[126:129]
	v_mfma_f32_16x16x32_bf16 v[122:125], v[142:145], v[150:153], v[122:125]
	v_mfma_f32_16x16x32_bf16 v[118:121], v[134:137], v[158:161], v[118:121]
	v_mfma_f32_16x16x32_bf16 v[110:113], v[142:145], v[158:161], v[110:113]
	v_mfma_f32_16x16x32_bf16 v[102:105], v[134:137], v[198:201], v[102:105]
	v_mfma_f32_16x16x32_bf16 v[94:97], v[142:145], v[198:201], v[94:97]
	v_mfma_f32_16x16x32_bf16 v[86:89], v[134:137], v[206:209], v[86:89]
	v_mfma_f32_16x16x32_bf16 v[78:81], v[142:145], v[206:209], v[78:81]
	v_mfma_f32_16x16x32_bf16 v[114:117], v[230:233], v[146:149], v[114:117]
	v_mfma_f32_16x16x32_bf16 v[106:109], v[238:241], v[146:149], v[106:109]
	v_mfma_f32_16x16x32_bf16 v[98:101], v[230:233], v[154:157], v[98:101]
	v_mfma_f32_16x16x32_bf16 v[90:93], v[238:241], v[154:157], v[90:93]
	v_mfma_f32_16x16x32_bf16 v[82:85], v[230:233], v[194:197], v[82:85]
	v_mfma_f32_16x16x32_bf16 v[74:77], v[238:241], v[194:197], v[74:77]
	v_mfma_f32_16x16x32_bf16 v[70:73], v[230:233], v[202:205], v[70:73]
	v_mfma_f32_16x16x32_bf16 v[66:69], v[238:241], v[202:205], v[66:69]
	v_mfma_f32_16x16x32_bf16 v[114:117], v[234:237], v[150:153], v[114:117]
	v_mfma_f32_16x16x32_bf16 v[106:109], v[242:245], v[150:153], v[106:109]
	v_mfma_f32_16x16x32_bf16 v[98:101], v[234:237], v[158:161], v[98:101]
	v_mfma_f32_16x16x32_bf16 v[90:93], v[242:245], v[158:161], v[90:93]
	v_mfma_f32_16x16x32_bf16 v[82:85], v[234:237], v[198:201], v[82:85]
	v_mfma_f32_16x16x32_bf16 v[74:77], v[242:245], v[198:201], v[74:77]
	v_mfma_f32_16x16x32_bf16 v[70:73], v[234:237], v[206:209], v[70:73]
	v_mfma_f32_16x16x32_bf16 v[66:69], v[242:245], v[206:209], v[66:69]
	s_setprio 0
	s_barrier
	ds_read_b128 v[146:149], v219 offset:49152
	ds_read_b128 v[150:153], v219 offset:50176
	ds_read_b128 v[154:157], v219 offset:51200
	ds_read_b128 v[158:161], v219 offset:52224
	ds_read_b128 v[194:197], v219 offset:53248
	ds_read_b128 v[198:201], v219 offset:54272
	ds_read_b128 v[202:205], v219 offset:55296
	ds_read_b128 v[206:209], v219 offset:56320
	s_add_i32 s1, s1, s4
	v_lshl_add_u64 v[176:177], v[176:177], 0, s[12:13]
	s_mov_b32 m0, s1
	s_nop 0
	global_load_lds_dwordx4 v[176:177], off
	v_lshl_add_u64 v[176:177], v[220:221], 0, s[12:13]
	s_add_i32 m0, s1, 0x2000
	s_nop 0
	global_load_lds_dwordx4 v[176:177], off
	s_mov_b32 m0, s34
	v_lshl_add_u64 v[176:177], v[246:247], 0, s[12:13]
	global_load_lds_dwordx4 v[176:177], off
	v_lshl_add_u64 v[176:177], v[248:249], 0, s[12:13]
	s_mov_b32 m0, s46
	s_nop 0
	global_load_lds_dwordx4 v[176:177], off
	s_add_u32 s22, s30, 0x40080
	s_addc_u32 s23, s31, 0
	s_add_i32 s1, s33, s4
	s_mov_b32 m0, s1
	s_nop 0
	global_load_lds_dwordx4 v0, s[22:23]
	s_add_i32 m0, s1, 0x2000
	s_nop 0
	global_load_lds_dwordx4 v178, s[22:23]
	s_waitcnt vmcnt(8)
	s_waitcnt lgkmcnt(0)
	s_barrier
	s_setprio 1
	v_mfma_f32_16x16x32_bf16 v[62:65], v[130:133], v[146:149], v[62:65]
	v_mfma_f32_16x16x32_bf16 v[58:61], v[138:141], v[146:149], v[58:61]
	v_mfma_f32_16x16x32_bf16 v[54:57], v[130:133], v[154:157], v[54:57]
	v_mfma_f32_16x16x32_bf16 v[46:49], v[138:141], v[154:157], v[46:49]
	v_mfma_f32_16x16x32_bf16 v[38:41], v[130:133], v[194:197], v[38:41]
	v_mfma_f32_16x16x32_bf16 v[30:33], v[138:141], v[194:197], v[30:33]
	v_mfma_f32_16x16x32_bf16 v[22:25], v[130:133], v[202:205], v[22:25]
	v_mfma_f32_16x16x32_bf16 v[14:17], v[138:141], v[202:205], v[14:17]
	v_mfma_f32_16x16x32_bf16 v[62:65], v[134:137], v[150:153], v[62:65]
	v_mfma_f32_16x16x32_bf16 v[58:61], v[142:145], v[150:153], v[58:61]
	v_mfma_f32_16x16x32_bf16 v[54:57], v[134:137], v[158:161], v[54:57]
	v_mfma_f32_16x16x32_bf16 v[46:49], v[142:145], v[158:161], v[46:49]
	v_mfma_f32_16x16x32_bf16 v[38:41], v[134:137], v[198:201], v[38:41]
	v_mfma_f32_16x16x32_bf16 v[30:33], v[142:145], v[198:201], v[30:33]
	v_mfma_f32_16x16x32_bf16 v[22:25], v[134:137], v[206:209], v[22:25]
	v_mfma_f32_16x16x32_bf16 v[14:17], v[142:145], v[206:209], v[14:17]
	v_mfma_f32_16x16x32_bf16 v[50:53], v[230:233], v[146:149], v[50:53]
	v_mfma_f32_16x16x32_bf16 v[42:45], v[238:241], v[146:149], v[42:45]
	v_mfma_f32_16x16x32_bf16 v[34:37], v[230:233], v[154:157], v[34:37]
	v_mfma_f32_16x16x32_bf16 v[26:29], v[238:241], v[154:157], v[26:29]
	v_mfma_f32_16x16x32_bf16 v[18:21], v[230:233], v[194:197], v[18:21]
	v_mfma_f32_16x16x32_bf16 v[10:13], v[238:241], v[194:197], v[10:13]
	v_mfma_f32_16x16x32_bf16 v[6:9], v[230:233], v[202:205], v[6:9]
	v_mfma_f32_16x16x32_bf16 v[2:5], v[238:241], v[202:205], v[2:5]
	v_mfma_f32_16x16x32_bf16 v[50:53], v[234:237], v[150:153], v[50:53]
	v_mfma_f32_16x16x32_bf16 v[42:45], v[242:245], v[150:153], v[42:45]
	v_mfma_f32_16x16x32_bf16 v[34:37], v[234:237], v[158:161], v[34:37]
	v_mfma_f32_16x16x32_bf16 v[26:29], v[242:245], v[158:161], v[26:29]
	v_mfma_f32_16x16x32_bf16 v[18:21], v[234:237], v[198:201], v[18:21]
	v_mfma_f32_16x16x32_bf16 v[10:13], v[242:245], v[198:201], v[10:13]
	v_mfma_f32_16x16x32_bf16 v[6:9], v[234:237], v[206:209], v[6:9]
	v_mfma_f32_16x16x32_bf16 v[2:5], v[242:245], v[206:209], v[2:5]
	s_setprio 0
	s_add_i32 s54, s54, 2
	s_add_u32 s42, s42, 0x100
	s_addc_u32 s43, s43, 0
	s_add_u32 s52, s52, 0x100
	s_addc_u32 s53, s53, 0
	s_cmp_gt_u32 s54, 13
	s_barrier
	s_cbranch_scc0 .LBB0_289
	v_lshl_add_u32 v208, s49, 8, v216
	v_ashrrev_i32_e32 v209, 31, v208
	v_lshlrev_b64 v[130:131], 6, v[208:209]
	v_or_b32_e32 v206, 16, v208
	v_lshl_add_u64 v[130:131], v[186:187], 0, v[130:131]
	v_ashrrev_i32_e32 v207, 31, v206
	global_load_dwordx4 v[154:157], v[130:131], off
	v_lshlrev_b64 v[130:131], 6, v[206:207]
	v_lshl_add_u64 v[130:131], v[186:187], 0, v[130:131]
	global_load_dwordx4 v[158:161], v[130:131], off
	v_or_b32_e32 v204, 32, v208
	v_ashrrev_i32_e32 v205, 31, v204
	v_lshlrev_b64 v[130:131], 6, v[204:205]
	v_or_b32_e32 v202, 48, v208
	v_lshl_add_u64 v[130:131], v[186:187], 0, v[130:131]
	v_ashrrev_i32_e32 v203, 31, v202
	global_load_dwordx4 v[150:153], v[130:131], off
	v_lshlrev_b64 v[130:131], 6, v[202:203]
	v_lshl_add_u64 v[130:131], v[186:187], 0, v[130:131]
	global_load_dwordx4 v[146:149], v[130:131], off
	v_add_u32_e32 v200, 0x80, v208
	v_ashrrev_i32_e32 v201, 31, v200
	v_lshlrev_b64 v[130:131], 6, v[200:201]
	v_add_u32_e32 v198, 0x90, v208
	v_lshl_add_u64 v[130:131], v[186:187], 0, v[130:131]
	v_ashrrev_i32_e32 v199, 31, v198
	global_load_dwordx4 v[142:145], v[130:131], off
	v_lshlrev_b64 v[130:131], 6, v[198:199]
	v_add_u32_e32 v196, 0xa0, v208
	v_lshl_add_u64 v[130:131], v[186:187], 0, v[130:131]
	v_ashrrev_i32_e32 v197, 31, v196
	global_load_dwordx4 v[138:141], v[130:131], off
	v_lshlrev_b64 v[130:131], 6, v[196:197]
	v_add_u32_e32 v194, 0xb0, v208
	v_lshl_add_u64 v[130:131], v[186:187], 0, v[130:131]
	v_ashrrev_i32_e32 v195, 31, v194
	global_load_dwordx4 v[134:137], v[130:131], off
	v_lshlrev_b64 v[130:131], 6, v[194:195]
	v_lshl_add_u64 v[130:131], v[186:187], 0, v[130:131]
	global_load_dwordx4 v[130:133], v[130:131], off
	v_and_b32_e32 v169, 64, v212
	v_xor_b32_e32 v168, 16, v212
	v_add_u32_e32 v169, 64, v169
	v_cmp_lt_i32_e32 vcc, v168, v169
	s_mov_b32 s22, 0x358637bd
	s_cmp_gt_i32 s48, 11
	v_cndmask_b32_e32 v168, v212, v168, vcc
	v_lshlrev_b32_e32 v221, 2, v168
	v_xor_b32_e32 v168, 32, v212
	v_cmp_lt_i32_e32 vcc, v168, v169
	s_cselect_b64 s[30:31], -1, 0
	v_readlane_b32 s50, v254, 42
	v_cndmask_b32_e32 v168, v212, v168, vcc
	v_lshlrev_b32_e32 v220, 2, v168
	s_mov_b64 s[44:45], -1
	s_movk_i32 s1, 0x1800
	s_movk_i32 s33, 0x7fff
	v_readlane_b32 s51, v254, 43
	s_waitcnt vmcnt(0)
	v_mov_b32_e32 v176, v155
	v_mov_b32_e32 v177, v156
	v_mov_b32_e32 v155, v157
	v_mov_b32_e32 v156, v159
	v_mov_b32_e32 v157, v160
	v_mov_b32_e32 v159, v161
	v_pk_add_f32 v[154:155], v[176:177], v[154:155]
	v_pk_add_f32 v[156:157], v[156:157], v[158:159]
	v_mov_b32_e32 v159, v154
	v_mov_b32_e32 v158, v156
	v_mov_b32_e32 v154, v157
	v_pk_add_f32 v[154:155], v[158:159], v[154:155]
	ds_bpermute_b32 v157, v221, v155
	ds_bpermute_b32 v156, v221, v154
	v_mov_b32_e32 v160, v151
	v_mov_b32_e32 v161, v152
	v_mov_b32_e32 v151, v153
	v_mov_b32_e32 v152, v147
	v_mov_b32_e32 v153, v148
	v_mov_b32_e32 v147, v149
	v_pk_add_f32 v[150:151], v[160:161], v[150:151]
	v_pk_add_f32 v[146:147], v[152:153], v[146:147]
	s_waitcnt lgkmcnt(0)
	v_pk_add_f32 v[154:155], v[154:155], v[156:157]
	v_mov_b32_e32 v148, v146
	v_mov_b32_e32 v149, v150
	v_mov_b32_e32 v150, v147
	ds_bpermute_b32 v157, v220, v155
	ds_bpermute_b32 v156, v220, v154
	v_pk_add_f32 v[146:147], v[148:149], v[150:151]
	ds_bpermute_b32 v149, v221, v147
	ds_bpermute_b32 v148, v221, v146
	v_mov_b64_e32 v[158:159], s[22:23]
	s_waitcnt lgkmcnt(2)
	v_pk_add_f32 v[154:155], v[154:155], v[156:157]
	s_mov_b32 s22, 0x3a800000
	v_pk_fma_f32 v[154:155], v[154:155], s[22:23], v[158:159] op_sel_hi:[1,0,0]
	s_waitcnt lgkmcnt(0)
	v_pk_add_f32 v[146:147], v[146:147], v[148:149]
	v_mul_f32_e32 v156, 0x4b800000, v155
	v_cmp_gt_f32_e64 s[42:43], s39, v155
	ds_bpermute_b32 v149, v220, v147
	ds_bpermute_b32 v148, v220, v146
	v_cndmask_b32_e64 v155, v155, v156, s[42:43]
	v_rsq_f32_e32 v155, v155
	v_mov_b32_e32 v150, v143
	v_mov_b32_e32 v151, v144
	v_mov_b32_e32 v143, v145
	v_mov_b32_e32 v144, v139
	v_mov_b32_e32 v145, v140
	v_mov_b32_e32 v139, v141
	s_waitcnt lgkmcnt(0)
	v_pk_add_f32 v[146:147], v[146:147], v[148:149]
	v_pk_add_f32 v[142:143], v[150:151], v[142:143]
	v_pk_add_f32 v[138:139], v[144:145], v[138:139]
	v_mul_f32_e32 v156, 0x45800000, v155
	v_pk_fma_f32 v[148:149], v[146:147], s[22:23], v[158:159] op_sel_hi:[1,0,0]
	v_mov_b32_e32 v140, v138
	v_mov_b32_e32 v141, v142
	v_mov_b32_e32 v142, v139
	v_cmp_gt_f32_e32 vcc, s39, v154
	v_cndmask_b32_e64 v156, v155, v156, s[42:43]
	v_mul_f32_e32 v155, 0x4b800000, v154
	v_mul_f32_e32 v146, 0x4b800000, v149
	v_cmp_gt_f32_e64 s[42:43], s39, v149
	v_pk_add_f32 v[138:139], v[140:141], v[142:143]
	v_mov_b32_e32 v142, v135
	v_mov_b32_e32 v143, v136
	v_mov_b32_e32 v135, v137
	v_mov_b32_e32 v136, v131
	v_mov_b32_e32 v137, v132
	v_mov_b32_e32 v131, v133
	v_cndmask_b32_e32 v154, v154, v155, vcc
	v_cndmask_b32_e64 v146, v149, v146, s[42:43]
	v_pk_add_f32 v[134:135], v[142:143], v[134:135]
	v_pk_add_f32 v[130:131], v[136:137], v[130:131]
	v_rsq_f32_e32 v154, v154
	v_rsq_f32_e32 v146, v146
	v_mov_b32_e32 v132, v130
	v_mov_b32_e32 v133, v134
	v_mov_b32_e32 v134, v131
	v_pk_add_f32 v[130:131], v[132:133], v[134:135]
	ds_bpermute_b32 v141, v221, v139
	ds_bpermute_b32 v140, v221, v138
	ds_bpermute_b32 v133, v221, v131
	ds_bpermute_b32 v132, v221, v130
	v_mul_f32_e32 v155, 0x45800000, v154
	v_mul_f32_e32 v147, 0x45800000, v146
	v_cndmask_b32_e32 v154, v154, v155, vcc
	v_cmp_gt_f32_e32 vcc, s39, v148
	v_cndmask_b32_e64 v146, v146, v147, s[42:43]
	v_mul_f32_e32 v147, 0x4b800000, v148
	v_cndmask_b32_e32 v147, v148, v147, vcc
	v_rsq_f32_e32 v147, v147
	s_waitcnt lgkmcnt(2)
	v_pk_add_f32 v[138:139], v[138:139], v[140:141]
	s_waitcnt lgkmcnt(0)
	v_pk_add_f32 v[132:133], v[130:131], v[132:133]
	ds_bpermute_b32 v141, v220, v139
	ds_bpermute_b32 v140, v220, v138
	ds_bpermute_b32 v135, v220, v133
	ds_bpermute_b32 v134, v220, v132
	v_mul_f32_e32 v148, 0x45800000, v147
	v_cndmask_b32_e64 v130, 0, 1, s[24:25]
	v_cndmask_b32_e32 v148, v147, v148, vcc
	s_and_b64 vcc, exec, s[30:31]
	v_cmp_ne_u32_e64 s[42:43], 1, v130
	s_cbranch_vccz .LBB0_294
	s_and_b64 vcc, exec, s[42:43]
	s_cbranch_vccnz .LBB0_293
	global_load_dwordx4 v[142:145], v[188:189], off
	v_lshlrev_b64 v[130:131], 7, v[208:209]
	v_lshl_add_u64 v[130:131], v[184:185], 0, v[130:131]
	s_waitcnt vmcnt(0)
	v_pk_fma_f32 v[144:145], v[128:129], v[156:157], v[144:145] op_sel_hi:[1,0,1]
	v_pk_fma_f32 v[142:143], v[126:127], v[156:157], v[142:143] op_sel_hi:[1,0,1]
	global_store_dwordx4 v[130:131], v[142:145], off
	global_load_dwordx4 v[142:145], v[188:189], off offset:16
	s_waitcnt vmcnt(0)
	v_pk_fma_f32 v[144:145], v[124:125], v[156:157], v[144:145] op_sel_hi:[1,0,1]
	v_pk_fma_f32 v[142:143], v[122:123], v[156:157], v[142:143] op_sel_hi:[1,0,1]
	global_store_dwordx4 v[130:131], v[142:145], off offset:16
	global_load_dwordx4 v[142:145], v[188:189], off
	v_lshlrev_b64 v[130:131], 7, v[206:207]
	v_lshl_add_u64 v[130:131], v[184:185], 0, v[130:131]
	s_waitcnt vmcnt(0)
	v_pk_fma_f32 v[144:145], v[120:121], v[154:155], v[144:145] op_sel_hi:[1,0,1]
	v_pk_fma_f32 v[142:143], v[118:119], v[154:155], v[142:143] op_sel_hi:[1,0,1]
	global_store_dwordx4 v[130:131], v[142:145], off
	global_load_dwordx4 v[142:145], v[188:189], off offset:16
	s_waitcnt vmcnt(0)
	v_pk_fma_f32 v[144:145], v[112:113], v[154:155], v[144:145] op_sel_hi:[1,0,1]
	v_pk_fma_f32 v[142:143], v[110:111], v[154:155], v[142:143] op_sel_hi:[1,0,1]
	global_store_dwordx4 v[130:131], v[142:145], off offset:16
	global_load_dwordx4 v[142:145], v[188:189], off
	v_lshlrev_b64 v[130:131], 7, v[204:205]
	v_lshl_add_u64 v[130:131], v[184:185], 0, v[130:131]
	s_waitcnt vmcnt(0)
	v_pk_fma_f32 v[144:145], v[104:105], v[146:147], v[144:145] op_sel_hi:[1,0,1]
	v_pk_fma_f32 v[142:143], v[102:103], v[146:147], v[142:143] op_sel_hi:[1,0,1]
	global_store_dwordx4 v[130:131], v[142:145], off
	global_load_dwordx4 v[142:145], v[188:189], off offset:16
	s_waitcnt vmcnt(0)
	v_pk_fma_f32 v[144:145], v[96:97], v[146:147], v[144:145] op_sel_hi:[1,0,1]
	v_pk_fma_f32 v[142:143], v[94:95], v[146:147], v[142:143] op_sel_hi:[1,0,1]
	global_store_dwordx4 v[130:131], v[142:145], off offset:16
	global_load_dwordx4 v[142:145], v[188:189], off
	v_lshlrev_b64 v[130:131], 7, v[202:203]
	v_lshl_add_u64 v[130:131], v[184:185], 0, v[130:131]
	s_waitcnt vmcnt(0)
	v_pk_fma_f32 v[144:145], v[88:89], v[148:149], v[144:145] op_sel_hi:[1,0,1]
	v_pk_fma_f32 v[142:143], v[86:87], v[148:149], v[142:143] op_sel_hi:[1,0,1]
	global_store_dwordx4 v[130:131], v[142:145], off
	global_load_dwordx4 v[142:145], v[188:189], off offset:16
	s_waitcnt vmcnt(0)
	v_pk_fma_f32 v[144:145], v[80:81], v[148:149], v[144:145] op_sel_hi:[1,0,1]
	v_pk_fma_f32 v[142:143], v[78:79], v[148:149], v[142:143] op_sel_hi:[1,0,1]
	global_store_dwordx4 v[130:131], v[142:145], off offset:16

.LBB0_357:
	v_bfe_u32 v18, v16, 4, 2
	s_and_b64 s[6:7], s[6:7], exec
	v_and_b32_e32 v17, 15, v16
	v_lshlrev_b32_e32 v19, 3, v18
	v_lshlrev_b32_e32 v18, 4, v18
	v_lshlrev_b32_e32 v16, 2, v16
	s_cselect_b32 s54, 0, 0x4000
	s_and_b32 s6, s8, 3
	v_lshl_or_b32 v159, s0, 6, v17
	v_lshl_or_b32 v17, v17, 6, v18
	s_lshl_b32 s0, s0, 13
	v_and_b32_e32 v16, 32, v16
	s_add_i32 m0, s49, 0x18000
	v_lshl_add_u64 v[8:9], v[8:9], 0, s[12:13]
	v_bitop3_b32 v20, v17, s0, v16 bitop3:0xde
	s_lshl_b32 s0, s6, 12
	s_waitcnt vmcnt(2)
	s_barrier
	global_load_lds_dwordx4 v[8:9], off
	v_lshl_add_u64 v[6:7], v[6:7], 0, s[12:13]
	s_add_i32 m0, s49, 0x1a000
	s_add_i32 s55, s49, 0x8000
	s_add_i32 s56, s49, 0xa000
	v_bitop3_b32 v181, v17, s0, v16 bitop3:0xde
	global_load_lds_dwordx4 v[6:7], off
	v_lshl_add_u64 v[4:5], v[4:5], 0, s[12:13]
	s_mov_b32 m0, s55
	s_add_u32 s0, s30, 0x40080
	global_load_lds_dwordx4 v[4:5], off
	v_lshl_add_u64 v[2:3], v[2:3], 0, s[12:13]
	s_mov_b32 m0, s56
	s_addc_u32 s1, s31, 0
	global_load_lds_dwordx4 v[2:3], off
	s_add_i32 m0, s49, 0x1c000
	v_lshl_add_u64 v[2:3], s[0:1], 0, v[0:1]
	global_load_lds_dwordx4 v[2:3], off
	v_lshl_add_u64 v[2:3], s[0:1], 0, v[138:139]
	s_add_i32 m0, s49, 0x1e000
	v_readlane_b32 s0, v254, 39
	global_load_lds_dwordx4 v[2:3], off
	v_lshlrev_b32_e32 v2, 14, v14
	v_and_b32_e32 v2, 0xffff8000, v2
	v_lshl_add_u32 v2, v13, 11, v2
	v_and_b32_e32 v3, 1, v14
	v_lshl_or_b32 v183, s6, 5, v19
	v_mov_b32_e32 v19, v1
	v_readlane_b32 s1, v254, 40
	v_lshl_or_b32 v2, v3, 6, v2
	v_lshl_add_u32 v150, v15, 1, v2
	v_lshl_add_u64 v[144:145], s[0:1], 0, v[18:19]
	v_readlane_b32 s0, v254, 44
	v_lshlrev_b32_e32 v2, 14, v10
	v_readlane_b32 s1, v254, 45
	v_and_b32_e32 v2, 0xffff8000, v2
	s_waitcnt vmcnt(6)
	v_lshl_add_u32 v2, v11, 11, v2
	v_lshl_add_u64 v[146:147], s[0:1], 0, v[18:19]
	v_readlane_b32 s0, v254, 46
	v_and_b32_e32 v3, 1, v10
	s_cmp_eq_u32 s6, 0
	v_readlane_b32 s1, v254, 47
	v_lshl_or_b32 v2, v3, 6, v2
	v_readlane_b32 s8, v253, 31
	s_mov_b32 s53, 0
	s_cselect_b64 s[6:7], -1, 0
	v_lshl_add_u64 v[148:149], s[0:1], 0, v[18:19]
	v_mov_b32_e32 v151, v1
	v_lshl_add_u32 v152, v12, 1, v2
	v_mov_b32_e32 v153, v1
	v_add_u32_e32 v185, 0, v20
	v_readlane_b32 s0, v253, 23
	s_mov_b32 s16, s8
	s_movk_i32 s57, 0x121
	s_mov_b32 s58, 0x3a800000
	s_mov_b32 s60, 0x358637bd
	s_barrier
	v_readlane_b32 s9, v253, 32
	s_branch .LBB0_359

.LBB0_362:
	s_add_u32 s1, s28, 0xfffc0080
	s_addc_u32 s22, s29, -1
	s_add_i32 s23, 0, 0x10000
	v_add_u32_e32 v158, s23, v181
	ds_read_b128 v[130:133], v158
	ds_read_b128 v[134:137], v158 offset:1024
	ds_read_b128 v[154:157], v158 offset:2048
	ds_read_b128 v[186:189], v158 offset:3072
	s_cmp_eq_u32 s44, 12
	s_cselect_b32 s43, s17, s22
	s_cselect_b32 s42, s20, s1
	s_cselect_b32 s31, s9, s34
	s_cselect_b32 s30, s21, s25
	v_lshl_add_u64 v[160:161], s[28:29], 0, v[150:151]
	s_add_i32 m0, s49, 0xc000
	ds_read_b128 v[190:193], v185
	ds_read_b128 v[194:197], v185 offset:1024
	ds_read_b128 v[198:201], v185 offset:2048
	ds_read_b128 v[202:205], v185 offset:3072
	ds_read_b128 v[206:209], v185 offset:4096
	ds_read_b128 v[216:219], v185 offset:5120
	ds_read_b128 v[230:233], v185 offset:6144
	ds_read_b128 v[234:237], v185 offset:7168
	global_load_lds_dwordx4 v[160:161], off
	v_lshl_add_u64 v[160:161], s[28:29], 0, v[152:153]
	s_add_i32 m0, s49, 0xe000
	s_nop 0
	global_load_lds_dwordx4 v[160:161], off
	s_add_i32 s1, 0, 0x14000
	v_add_u32_e32 v158, s1, v181
	ds_read_b128 v[238:241], v158
	ds_read_b128 v[242:245], v158 offset:1024
	ds_read_b128 v[246:249], v158 offset:2048
	ds_read_b128 v[176:179], v158 offset:3072
	s_waitcnt vmcnt(8)
	s_waitcnt lgkmcnt(0)
	s_barrier
	s_setprio 1
	v_mfma_f32_16x16x32_bf16 v[126:129], v[130:133], v[190:193], v[126:129]
	v_mfma_f32_16x16x32_bf16 v[122:125], v[154:157], v[190:193], v[122:125]
	v_mfma_f32_16x16x32_bf16 v[110:113], v[130:133], v[198:201], v[110:113]
	v_mfma_f32_16x16x32_bf16 v[106:109], v[154:157], v[198:201], v[106:109]
	v_mfma_f32_16x16x32_bf16 v[94:97], v[130:133], v[206:209], v[94:97]
	v_mfma_f32_16x16x32_bf16 v[90:93], v[154:157], v[206:209], v[90:93]
	v_mfma_f32_16x16x32_bf16 v[78:81], v[130:133], v[230:233], v[78:81]
	v_mfma_f32_16x16x32_bf16 v[74:77], v[154:157], v[230:233], v[74:77]
	v_mfma_f32_16x16x32_bf16 v[126:129], v[134:137], v[194:197], v[126:129]
	v_mfma_f32_16x16x32_bf16 v[122:125], v[186:189], v[194:197], v[122:125]
	v_mfma_f32_16x16x32_bf16 v[110:113], v[134:137], v[202:205], v[110:113]
	v_mfma_f32_16x16x32_bf16 v[106:109], v[186:189], v[202:205], v[106:109]
	v_mfma_f32_16x16x32_bf16 v[94:97], v[134:137], v[216:219], v[94:97]
	v_mfma_f32_16x16x32_bf16 v[90:93], v[186:189], v[216:219], v[90:93]
	v_mfma_f32_16x16x32_bf16 v[78:81], v[134:137], v[234:237], v[78:81]
	v_mfma_f32_16x16x32_bf16 v[74:77], v[186:189], v[234:237], v[74:77]
	v_mfma_f32_16x16x32_bf16 v[118:121], v[238:241], v[190:193], v[118:121]
	v_mfma_f32_16x16x32_bf16 v[114:117], v[246:249], v[190:193], v[114:117]
	v_mfma_f32_16x16x32_bf16 v[102:105], v[238:241], v[198:201], v[102:105]
	v_mfma_f32_16x16x32_bf16 v[98:101], v[246:249], v[198:201], v[98:101]
	v_mfma_f32_16x16x32_bf16 v[86:89], v[238:241], v[206:209], v[86:89]
	v_mfma_f32_16x16x32_bf16 v[82:85], v[246:249], v[206:209], v[82:85]
	v_mfma_f32_16x16x32_bf16 v[70:73], v[238:241], v[230:233], v[70:73]
	v_mfma_f32_16x16x32_bf16 v[66:69], v[246:249], v[230:233], v[66:69]
	v_mfma_f32_16x16x32_bf16 v[118:121], v[242:245], v[194:197], v[118:121]
	v_mfma_f32_16x16x32_bf16 v[114:117], v[176:179], v[194:197], v[114:117]
	v_mfma_f32_16x16x32_bf16 v[102:105], v[242:245], v[202:205], v[102:105]
	v_mfma_f32_16x16x32_bf16 v[98:101], v[176:179], v[202:205], v[98:101]
	v_mfma_f32_16x16x32_bf16 v[86:89], v[242:245], v[216:219], v[86:89]
	v_mfma_f32_16x16x32_bf16 v[82:85], v[176:179], v[216:219], v[82:85]
	v_mfma_f32_16x16x32_bf16 v[70:73], v[242:245], v[234:237], v[70:73]
	v_mfma_f32_16x16x32_bf16 v[66:69], v[176:179], v[234:237], v[66:69]
	s_setprio 0
	s_barrier
	ds_read_b128 v[190:193], v185 offset:16384
	ds_read_b128 v[194:197], v185 offset:17408
	ds_read_b128 v[198:201], v185 offset:18432
	ds_read_b128 v[202:205], v185 offset:19456
	ds_read_b128 v[206:209], v185 offset:20480
	ds_read_b128 v[216:219], v185 offset:21504
	ds_read_b128 v[230:233], v185 offset:22528
	ds_read_b128 v[234:237], v185 offset:23552
	s_add_i32 s22, s23, s48
	v_lshl_add_u64 v[160:161], s[30:31], 0, v[0:1]
	s_mov_b32 m0, s22
	s_nop 0
	global_load_lds_dwordx4 v[160:161], off
	v_lshl_add_u64 v[220:221], s[30:31], 0, v[138:139]
	s_add_i32 m0, s22, 0x2000
	s_nop 0
	global_load_lds_dwordx4 v[220:221], off
	s_mov_b32 m0, s49
	v_lshl_add_u64 v[250:251], s[42:43], 0, v[142:143]
	global_load_lds_dwordx4 v[250:251], off
	v_lshl_add_u64 v[168:169], s[42:43], 0, v[140:141]
	s_mov_b32 m0, s50
	s_nop 0
	global_load_lds_dwordx4 v[168:169], off
	s_add_u32 s22, s30, 0x40000
	s_addc_u32 s23, s31, 0
	s_add_i32 s1, s1, s48
	s_mov_b32 m0, s1
	s_nop 0
	global_load_lds_dwordx4 v0, s[22:23]
	s_add_i32 m0, s1, 0x2000
	s_nop 0
	global_load_lds_dwordx4 v138, s[22:23]
	s_waitcnt vmcnt(8)
	s_waitcnt lgkmcnt(0)
	s_barrier
	s_setprio 1
	v_mfma_f32_16x16x32_bf16 v[62:65], v[130:133], v[190:193], v[62:65]
	v_mfma_f32_16x16x32_bf16 v[58:61], v[154:157], v[190:193], v[58:61]
	v_mfma_f32_16x16x32_bf16 v[46:49], v[130:133], v[198:201], v[46:49]
	v_mfma_f32_16x16x32_bf16 v[42:45], v[154:157], v[198:201], v[42:45]
	v_mfma_f32_16x16x32_bf16 v[30:33], v[130:133], v[206:209], v[30:33]
	v_mfma_f32_16x16x32_bf16 v[26:29], v[154:157], v[206:209], v[26:29]
	v_mfma_f32_16x16x32_bf16 v[14:17], v[130:133], v[230:233], v[14:17]
	v_mfma_f32_16x16x32_bf16 v[10:13], v[154:157], v[230:233], v[10:13]
	v_mfma_f32_16x16x32_bf16 v[62:65], v[134:137], v[194:197], v[62:65]
	v_mfma_f32_16x16x32_bf16 v[58:61], v[186:189], v[194:197], v[58:61]
	v_mfma_f32_16x16x32_bf16 v[46:49], v[134:137], v[202:205], v[46:49]
	v_mfma_f32_16x16x32_bf16 v[42:45], v[186:189], v[202:205], v[42:45]
	v_mfma_f32_16x16x32_bf16 v[30:33], v[134:137], v[216:219], v[30:33]
	v_mfma_f32_16x16x32_bf16 v[26:29], v[186:189], v[216:219], v[26:29]
	v_mfma_f32_16x16x32_bf16 v[14:17], v[134:137], v[234:237], v[14:17]
	v_mfma_f32_16x16x32_bf16 v[10:13], v[186:189], v[234:237], v[10:13]
	v_mfma_f32_16x16x32_bf16 v[54:57], v[238:241], v[190:193], v[54:57]
	v_mfma_f32_16x16x32_bf16 v[50:53], v[246:249], v[190:193], v[50:53]
	v_mfma_f32_16x16x32_bf16 v[38:41], v[238:241], v[198:201], v[38:41]
	v_mfma_f32_16x16x32_bf16 v[34:37], v[246:249], v[198:201], v[34:37]
	v_mfma_f32_16x16x32_bf16 v[22:25], v[238:241], v[206:209], v[22:25]
	v_mfma_f32_16x16x32_bf16 v[18:21], v[246:249], v[206:209], v[18:21]
	v_mfma_f32_16x16x32_bf16 v[6:9], v[238:241], v[230:233], v[6:9]
	v_mfma_f32_16x16x32_bf16 v[2:5], v[246:249], v[230:233], v[2:5]
	v_mfma_f32_16x16x32_bf16 v[54:57], v[242:245], v[194:197], v[54:57]
	v_mfma_f32_16x16x32_bf16 v[50:53], v[176:179], v[194:197], v[50:53]
	v_mfma_f32_16x16x32_bf16 v[38:41], v[242:245], v[202:205], v[38:41]
	v_mfma_f32_16x16x32_bf16 v[34:37], v[176:179], v[202:205], v[34:37]
	v_mfma_f32_16x16x32_bf16 v[22:25], v[242:245], v[216:219], v[22:25]
	v_mfma_f32_16x16x32_bf16 v[18:21], v[176:179], v[216:219], v[18:21]
	v_mfma_f32_16x16x32_bf16 v[6:9], v[242:245], v[234:237], v[6:9]
	v_mfma_f32_16x16x32_bf16 v[2:5], v[176:179], v[234:237], v[2:5]
	s_setprio 0
	s_barrier
	s_add_i32 s1, 0, 0x18000
	v_add_u32_e32 v158, s1, v181
	ds_read_b128 v[130:133], v158
	ds_read_b128 v[134:137], v158 offset:1024
	ds_read_b128 v[154:157], v158 offset:2048
	ds_read_b128 v[176:179], v158 offset:3072
	s_add_u32 s22, s42, 0x40000
	s_addc_u32 s23, s43, 0
	s_mov_b32 m0, s51
	v_lshl_add_u64 v[234:235], s[22:23], 0, v[142:143]
	ds_read_b128 v[186:189], v185 offset:32768
	ds_read_b128 v[190:193], v185 offset:33792
	ds_read_b128 v[194:197], v185 offset:34816
	ds_read_b128 v[198:201], v185 offset:35840
	ds_read_b128 v[202:205], v185 offset:36864
	ds_read_b128 v[206:209], v185 offset:37888
	ds_read_b128 v[216:219], v185 offset:38912
	ds_read_b128 v[230:233], v185 offset:39936
	global_load_lds_dwordx4 v[234:235], off
	v_lshl_add_u64 v[234:235], s[22:23], 0, v[140:141]
	s_mov_b32 m0, s52
	s_nop 0
	global_load_lds_dwordx4 v[234:235], off
	s_add_i32 s33, 0, 0x1c000
	v_add_u32_e32 v158, s33, v181
	ds_read_b128 v[234:237], v158
	ds_read_b128 v[238:241], v158 offset:1024
	ds_read_b128 v[242:245], v158 offset:2048
	ds_read_b128 v[246:249], v158 offset:3072
	s_waitcnt vmcnt(8)
	s_waitcnt lgkmcnt(0)
	s_barrier
	s_setprio 1
	v_mfma_f32_16x16x32_bf16 v[126:129], v[130:133], v[186:189], v[126:129]
	v_mfma_f32_16x16x32_bf16 v[122:125], v[154:157], v[186:189], v[122:125]
	v_mfma_f32_16x16x32_bf16 v[110:113], v[130:133], v[194:197], v[110:113]
	v_mfma_f32_16x16x32_bf16 v[106:109], v[154:157], v[194:197], v[106:109]
	v_mfma_f32_16x16x32_bf16 v[94:97], v[130:133], v[202:205], v[94:97]
	v_mfma_f32_16x16x32_bf16 v[90:93], v[154:157], v[202:205], v[90:93]
	v_mfma_f32_16x16x32_bf16 v[78:81], v[130:133], v[216:219], v[78:81]
	v_mfma_f32_16x16x32_bf16 v[74:77], v[154:157], v[216:219], v[74:77]
	v_mfma_f32_16x16x32_bf16 v[126:129], v[134:137], v[190:193], v[126:129]
	v_mfma_f32_16x16x32_bf16 v[122:125], v[176:179], v[190:193], v[122:125]
	v_mfma_f32_16x16x32_bf16 v[110:113], v[134:137], v[198:201], v[110:113]
	v_mfma_f32_16x16x32_bf16 v[106:109], v[176:179], v[198:201], v[106:109]
	v_mfma_f32_16x16x32_bf16 v[94:97], v[134:137], v[206:209], v[94:97]
	v_mfma_f32_16x16x32_bf16 v[90:93], v[176:179], v[206:209], v[90:93]
	v_mfma_f32_16x16x32_bf16 v[78:81], v[134:137], v[230:233], v[78:81]
	v_mfma_f32_16x16x32_bf16 v[74:77], v[176:179], v[230:233], v[74:77]
	v_mfma_f32_16x16x32_bf16 v[118:121], v[234:237], v[186:189], v[118:121]
	v_mfma_f32_16x16x32_bf16 v[114:117], v[242:245], v[186:189], v[114:117]
	v_mfma_f32_16x16x32_bf16 v[102:105], v[234:237], v[194:197], v[102:105]
	v_mfma_f32_16x16x32_bf16 v[98:101], v[242:245], v[194:197], v[98:101]
	v_mfma_f32_16x16x32_bf16 v[86:89], v[234:237], v[202:205], v[86:89]
	v_mfma_f32_16x16x32_bf16 v[82:85], v[242:245], v[202:205], v[82:85]
	v_mfma_f32_16x16x32_bf16 v[70:73], v[234:237], v[216:219], v[70:73]
	v_mfma_f32_16x16x32_bf16 v[66:69], v[242:245], v[216:219], v[66:69]
	v_mfma_f32_16x16x32_bf16 v[118:121], v[238:241], v[190:193], v[118:121]
	v_mfma_f32_16x16x32_bf16 v[114:117], v[246:249], v[190:193], v[114:117]
	v_mfma_f32_16x16x32_bf16 v[102:105], v[238:241], v[198:201], v[102:105]
	v_mfma_f32_16x16x32_bf16 v[98:101], v[246:249], v[198:201], v[98:101]
	v_mfma_f32_16x16x32_bf16 v[86:89], v[238:241], v[206:209], v[86:89]
	v_mfma_f32_16x16x32_bf16 v[82:85], v[246:249], v[206:209], v[82:85]
	v_mfma_f32_16x16x32_bf16 v[70:73], v[238:241], v[230:233], v[70:73]
	v_mfma_f32_16x16x32_bf16 v[66:69], v[246:249], v[230:233], v[66:69]
	s_setprio 0
	s_barrier
	ds_read_b128 v[186:189], v185 offset:49152
	ds_read_b128 v[190:193], v185 offset:50176
	ds_read_b128 v[194:197], v185 offset:51200
	ds_read_b128 v[198:201], v185 offset:52224
	ds_read_b128 v[202:205], v185 offset:53248
	ds_read_b128 v[206:209], v185 offset:54272
	ds_read_b128 v[216:219], v185 offset:55296
	ds_read_b128 v[230:233], v185 offset:56320
	s_add_i32 s1, s1, s48
	v_lshl_add_u64 v[160:161], v[160:161], 0, s[12:13]
	s_mov_b32 m0, s1
	s_nop 0
	global_load_lds_dwordx4 v[160:161], off
	v_lshl_add_u64 v[160:161], v[220:221], 0, s[12:13]
	s_add_i32 m0, s1, 0x2000
	s_nop 0
	global_load_lds_dwordx4 v[160:161], off
	s_mov_b32 m0, s55
	v_lshl_add_u64 v[160:161], v[250:251], 0, s[12:13]
	global_load_lds_dwordx4 v[160:161], off
	v_lshl_add_u64 v[160:161], v[168:169], 0, s[12:13]
	s_mov_b32 m0, s56
	s_nop 0
	global_load_lds_dwordx4 v[160:161], off
	s_add_u32 s22, s30, 0x40080
	s_addc_u32 s23, s31, 0
	s_add_i32 s1, s33, s48
	s_mov_b32 m0, s1
	s_nop 0
	global_load_lds_dwordx4 v0, s[22:23]
	s_add_i32 m0, s1, 0x2000
	s_nop 0
	global_load_lds_dwordx4 v138, s[22:23]
	s_waitcnt vmcnt(8)
	s_waitcnt lgkmcnt(0)
	s_barrier
	s_setprio 1
	v_mfma_f32_16x16x32_bf16 v[62:65], v[130:133], v[186:189], v[62:65]
	v_mfma_f32_16x16x32_bf16 v[58:61], v[154:157], v[186:189], v[58:61]
	v_mfma_f32_16x16x32_bf16 v[46:49], v[130:133], v[194:197], v[46:49]
	v_mfma_f32_16x16x32_bf16 v[42:45], v[154:157], v[194:197], v[42:45]
	v_mfma_f32_16x16x32_bf16 v[30:33], v[130:133], v[202:205], v[30:33]
	v_mfma_f32_16x16x32_bf16 v[26:29], v[154:157], v[202:205], v[26:29]
	v_mfma_f32_16x16x32_bf16 v[14:17], v[130:133], v[216:219], v[14:17]
	v_mfma_f32_16x16x32_bf16 v[10:13], v[154:157], v[216:219], v[10:13]
	v_mfma_f32_16x16x32_bf16 v[62:65], v[134:137], v[190:193], v[62:65]
	v_mfma_f32_16x16x32_bf16 v[58:61], v[176:179], v[190:193], v[58:61]
	v_mfma_f32_16x16x32_bf16 v[46:49], v[134:137], v[198:201], v[46:49]
	v_mfma_f32_16x16x32_bf16 v[42:45], v[176:179], v[198:201], v[42:45]
	v_mfma_f32_16x16x32_bf16 v[30:33], v[134:137], v[206:209], v[30:33]
	v_mfma_f32_16x16x32_bf16 v[26:29], v[176:179], v[206:209], v[26:29]
	v_mfma_f32_16x16x32_bf16 v[14:17], v[134:137], v[230:233], v[14:17]
	v_mfma_f32_16x16x32_bf16 v[10:13], v[176:179], v[230:233], v[10:13]
	v_mfma_f32_16x16x32_bf16 v[54:57], v[234:237], v[186:189], v[54:57]
	v_mfma_f32_16x16x32_bf16 v[50:53], v[242:245], v[186:189], v[50:53]
	v_mfma_f32_16x16x32_bf16 v[38:41], v[234:237], v[194:197], v[38:41]
	v_mfma_f32_16x16x32_bf16 v[34:37], v[242:245], v[194:197], v[34:37]
	v_mfma_f32_16x16x32_bf16 v[22:25], v[234:237], v[202:205], v[22:25]
	v_mfma_f32_16x16x32_bf16 v[18:21], v[242:245], v[202:205], v[18:21]
	v_mfma_f32_16x16x32_bf16 v[6:9], v[234:237], v[216:219], v[6:9]
	v_mfma_f32_16x16x32_bf16 v[2:5], v[242:245], v[216:219], v[2:5]
	v_mfma_f32_16x16x32_bf16 v[54:57], v[238:241], v[190:193], v[54:57]
	v_mfma_f32_16x16x32_bf16 v[50:53], v[246:249], v[190:193], v[50:53]
	v_mfma_f32_16x16x32_bf16 v[38:41], v[238:241], v[198:201], v[38:41]
	v_mfma_f32_16x16x32_bf16 v[34:37], v[246:249], v[198:201], v[34:37]
	v_mfma_f32_16x16x32_bf16 v[22:25], v[238:241], v[206:209], v[22:25]
	v_mfma_f32_16x16x32_bf16 v[18:21], v[246:249], v[206:209], v[18:21]
	v_mfma_f32_16x16x32_bf16 v[6:9], v[238:241], v[230:233], v[6:9]
	v_mfma_f32_16x16x32_bf16 v[2:5], v[246:249], v[230:233], v[2:5]
	s_setprio 0
	s_add_i32 s44, s44, 2
	s_add_u32 s28, s28, 0x100
	s_addc_u32 s29, s29, 0
	s_add_u32 s25, s25, 0x100
	s_addc_u32 s34, s34, 0
	s_cmp_gt_u32 s44, 13
	s_barrier
	s_cbranch_scc0 .LBB0_362
	v_and_b32_e32 v131, 64, v212
	v_xor_b32_e32 v130, 16, v212
	v_add_u32_e32 v131, 64, v131
	v_lshl_add_u32 v190, s16, 8, v159
	v_cmp_lt_i32_e32 vcc, v130, v131
	v_add_u32_e32 v156, s54, v190
	v_or_b32_e32 v134, 16, v156
	v_cndmask_b32_e32 v130, v212, v130, vcc
	v_lshlrev_b32_e32 v191, 2, v130
	v_xor_b32_e32 v130, 32, v212
	v_cmp_lt_i32_e32 vcc, v130, v131
	v_ashrrev_i32_e32 v157, 31, v156
	v_ashrrev_i32_e32 v135, 31, v134
	v_cndmask_b32_e32 v130, v212, v130, vcc
	v_lshlrev_b64 v[136:137], 6, v[156:157]
	v_lshlrev_b64 v[134:135], 6, v[134:135]
	v_lshlrev_b32_e32 v192, 2, v130
	v_lshl_add_u64 v[130:131], v[144:145], 0, v[136:137]
	v_lshl_add_u64 v[160:161], v[144:145], 0, v[134:135]
	global_load_dwordx4 v[130:133], v[130:131], off
	v_lshl_or_b32 v154, s0, 8, v183
	global_load_dwordx4 v[186:189], v[160:161], off
	v_or_b32_e32 v160, 32, v156
	v_ashrrev_i32_e32 v161, 31, v160
	v_lshlrev_b64 v[178:179], 6, v[160:161]
	v_or_b32_e32 v156, 48, v156
	v_lshl_add_u64 v[160:161], v[144:145], 0, v[178:179]
	v_ashrrev_i32_e32 v157, 31, v156
	global_load_dwordx4 v[194:197], v[160:161], off
	v_lshlrev_b64 v[160:161], 6, v[156:157]
	v_lshl_add_u64 v[156:157], v[144:145], 0, v[160:161]
	global_load_dwordx4 v[198:201], v[156:157], off
	s_ashr_i32 s0, s0, 2
	s_mul_hi_i32 s1, s0, 0x55555556
	s_lshr_b32 s9, s1, 31
	s_add_i32 s1, s1, s9
	s_mul_i32 s1, s1, 3
	s_sub_i32 s0, s0, s1
	s_cmp_lt_i32 s0, 2
	s_cselect_b64 s[0:1], -1, 0
	s_and_b64 s[28:29], s[6:7], s[0:1]
	v_ashrrev_i32_e32 v155, 31, v154
	s_mov_b64 s[44:45], -1
	v_or_b32_e32 v193, 48, v190
	s_waitcnt vmcnt(0)
	v_mov_b32_e32 v156, v131
	v_mov_b32_e32 v157, v132
	v_mov_b32_e32 v131, v133
	v_mov_b32_e32 v132, v187
	v_mov_b32_e32 v133, v188
	v_mov_b32_e32 v187, v189
	v_pk_add_f32 v[130:131], v[156:157], v[130:131]
	v_pk_add_f32 v[132:133], v[132:133], v[186:187]
	v_mov_b32_e32 v157, v130
	v_mov_b32_e32 v156, v132
	v_mov_b32_e32 v130, v133
	v_pk_add_f32 v[130:131], v[156:157], v[130:131]
	ds_bpermute_b32 v133, v191, v131
	ds_bpermute_b32 v132, v191, v130
	v_mov_b32_e32 v157, v200
	s_waitcnt lgkmcnt(0)
	v_pk_add_f32 v[130:131], v[130:131], v[132:133]
	ds_bpermute_b32 v133, v192, v131
	ds_bpermute_b32 v132, v192, v130
	s_waitcnt lgkmcnt(0)
	v_pk_add_f32 v[130:131], v[130:131], v[132:133]
	v_mov_b64_e32 v[132:133], s[60:61]
	v_pk_fma_f32 v[130:131], v[130:131], s[58:59], v[132:133] op_sel_hi:[1,0,0]
	s_nop 0
	v_mul_f32_e32 v156, 0x4b800000, v131
	v_cmp_gt_f32_e64 s[42:43], s39, v131
	v_cmp_gt_f32_e32 vcc, s39, v130
	s_nop 0
	v_cndmask_b32_e64 v131, v131, v156, s[42:43]
	v_rsq_f32_e32 v131, v131
	s_nop 0
	v_mul_f32_e32 v156, 0x45800000, v131
	v_cndmask_b32_e64 v184, v131, v156, s[42:43]
	v_mul_f32_e32 v131, 0x4b800000, v130
	v_cndmask_b32_e32 v130, v130, v131, vcc
	v_rsq_f32_e32 v130, v130
	v_mov_b32_e32 v156, v199
	v_mov_b32_e32 v199, v201
	v_pk_add_f32 v[156:157], v[156:157], v[198:199]
	v_mul_f32_e32 v131, 0x45800000, v130
	v_cndmask_b32_e32 v182, v130, v131, vcc
	v_mov_b32_e32 v130, v195
	v_mov_b32_e32 v131, v196
	v_mov_b32_e32 v195, v197
	v_pk_add_f32 v[130:131], v[130:131], v[194:195]
	v_mov_b32_e32 v176, v156
	v_mov_b32_e32 v177, v130
	v_mov_b32_e32 v130, v157
	v_pk_add_f32 v[130:131], v[176:177], v[130:131]
	ds_bpermute_b32 v157, v191, v131
	ds_bpermute_b32 v156, v191, v130
	v_or_b32_e32 v195, 16, v190
	v_or_b32_e32 v194, 32, v190
	s_waitcnt lgkmcnt(0)
	v_pk_add_f32 v[130:131], v[130:131], v[156:157]
	ds_bpermute_b32 v157, v192, v131
	ds_bpermute_b32 v156, v192, v130
	s_waitcnt lgkmcnt(0)
	v_pk_add_f32 v[130:131], v[130:131], v[156:157]
	s_nop 0
	v_pk_fma_f32 v[130:131], v[130:131], s[58:59], v[132:133] op_sel_hi:[1,0,0]
	v_lshlrev_b64 v[156:157], 1, v[154:155]
	v_mul_f32_e32 v132, 0x4b800000, v131
	v_cmp_gt_f32_e64 s[42:43], s39, v131
	v_cmp_gt_f32_e32 vcc, s39, v130
	s_nop 0
	v_cndmask_b32_e64 v131, v131, v132, s[42:43]
	v_rsq_f32_e32 v131, v131
	s_nop 0
	v_mul_f32_e32 v132, 0x45800000, v131
	v_cndmask_b32_e64 v180, v131, v132, s[42:43]
	v_mul_f32_e32 v131, 0x4b800000, v130
	v_cndmask_b32_e32 v130, v130, v131, vcc
	v_rsq_f32_e32 v130, v130
	s_nop 0
	v_mul_f32_e32 v131, 0x45800000, v130
	v_cndmask_b32_e32 v158, v130, v131, vcc
	s_and_b64 vcc, exec, s[28:29]
	s_cbranch_vccnz .LBB0_365
	v_mov_b64_e32 v[176:177], s[68:69]
	v_mad_i64_i32 v[130:131], s[0:1], v190, s86, v[176:177]
	v_lshl_add_u64 v[186:187], v[130:131], 0, v[156:157]
	v_pk_mul_f32 v[132:133], v[128:129], v[184:185] op_sel_hi:[1,0]
	v_pk_mul_f32 v[130:131], v[126:127], v[184:185] op_sel_hi:[1,0]
	v_pk_mul_f32 v[188:189], v[124:125], v[184:185] op_sel_hi:[1,0]
	v_pk_mul_f32 v[196:197], v[122:123], v[184:185] op_sel_hi:[1,0]
	v_cvt_pk_bf16_f32 v130, v130, v131
	v_cvt_pk_bf16_f32 v131, v132, v133
	v_cvt_pk_bf16_f32 v132, v196, v197
	v_cvt_pk_bf16_f32 v133, v188, v189
	global_store_dwordx4 v[186:187], v[130:133], off
	v_pk_mul_f32 v[188:189], v[116:117], v[184:185] op_sel_hi:[1,0]
	v_pk_mul_f32 v[196:197], v[114:115], v[184:185] op_sel_hi:[1,0]
	v_pk_mul_f32 v[132:133], v[120:121], v[184:185] op_sel_hi:[1,0]
	v_pk_mul_f32 v[130:131], v[118:119], v[184:185] op_sel_hi:[1,0]
	s_mov_b64 s[44:45], 0
	v_cvt_pk_bf16_f32 v130, v130, v131
	v_cvt_pk_bf16_f32 v131, v132, v133
	v_cvt_pk_bf16_f32 v132, v196, v197
	v_cvt_pk_bf16_f32 v133, v188, v189
	global_store_dwordx4 v[186:187], v[130:133], off offset:256
	v_pk_mul_f32 v[188:189], v[108:109], v[182:183] op_sel_hi:[1,0]
	v_pk_mul_f32 v[196:197], v[106:107], v[182:183] op_sel_hi:[1,0]
	v_mad_i64_i32 v[130:131], s[0:1], v195, s86, v[176:177]
	v_lshl_add_u64 v[186:187], v[130:131], 0, v[156:157]
	v_pk_mul_f32 v[132:133], v[112:113], v[182:183] op_sel_hi:[1,0]
	v_pk_mul_f32 v[130:131], v[110:111], v[182:183] op_sel_hi:[1,0]
	s_nop 0
	v_cvt_pk_bf16_f32 v130, v130, v131
	v_cvt_pk_bf16_f32 v131, v132, v133
	v_cvt_pk_bf16_f32 v132, v196, v197
	v_cvt_pk_bf16_f32 v133, v188, v189
	global_store_dwordx4 v[186:187], v[130:133], off
	v_pk_mul_f32 v[188:189], v[100:101], v[182:183] op_sel_hi:[1,0]
	v_pk_mul_f32 v[196:197], v[98:99], v[182:183] op_sel_hi:[1,0]
	v_pk_mul_f32 v[132:133], v[104:105], v[182:183] op_sel_hi:[1,0]
	v_pk_mul_f32 v[130:131], v[102:103], v[182:183] op_sel_hi:[1,0]
	s_nop 0
	v_cvt_pk_bf16_f32 v130, v130, v131
	v_cvt_pk_bf16_f32 v131, v132, v133
	v_cvt_pk_bf16_f32 v132, v196, v197
	v_cvt_pk_bf16_f32 v133, v188, v189
	global_store_dwordx4 v[186:187], v[130:133], off offset:256
	v_pk_mul_f32 v[188:189], v[92:93], v[180:181] op_sel_hi:[1,0]
	v_pk_mul_f32 v[196:197], v[90:91], v[180:181] op_sel_hi:[1,0]
	v_mad_i64_i32 v[130:131], s[0:1], v194, s86, v[176:177]
	v_lshl_add_u64 v[186:187], v[130:131], 0, v[156:157]
	v_pk_mul_f32 v[132:133], v[96:97], v[180:181] op_sel_hi:[1,0]
	v_pk_mul_f32 v[130:131], v[94:95], v[180:181] op_sel_hi:[1,0]
	s_nop 0
	v_cvt_pk_bf16_f32 v130, v130, v131
	v_cvt_pk_bf16_f32 v131, v132, v133
	v_cvt_pk_bf16_f32 v132, v196, v197
	v_cvt_pk_bf16_f32 v133, v188, v189
	global_store_dwordx4 v[186:187], v[130:133], off
	v_pk_mul_f32 v[188:189], v[84:85], v[180:181] op_sel_hi:[1,0]
	v_pk_mul_f32 v[196:197], v[82:83], v[180:181] op_sel_hi:[1,0]
	v_pk_mul_f32 v[132:133], v[88:89], v[180:181] op_sel_hi:[1,0]
	v_pk_mul_f32 v[130:131], v[86:87], v[180:181] op_sel_hi:[1,0]
	s_nop 0
	v_cvt_pk_bf16_f32 v130, v130, v131
	v_cvt_pk_bf16_f32 v131, v132, v133
	v_cvt_pk_bf16_f32 v132, v196, v197
	v_cvt_pk_bf16_f32 v133, v188, v189
	global_store_dwordx4 v[186:187], v[130:133], off offset:256
	v_pk_mul_f32 v[186:187], v[76:77], v[158:159] op_sel_hi:[1,0]
	v_pk_mul_f32 v[196:197], v[74:75], v[158:159] op_sel_hi:[1,0]
	v_mad_i64_i32 v[130:131], s[0:1], v193, s86, v[176:177]
	v_lshl_add_u64 v[176:177], v[130:131], 0, v[156:157]
	v_pk_mul_f32 v[132:133], v[80:81], v[158:159] op_sel_hi:[1,0]
	v_pk_mul_f32 v[130:131], v[78:79], v[158:159] op_sel_hi:[1,0]
	v_mad_i64_i32 v[188:189], s[0:1], v193, s86, 0
	v_cvt_pk_bf16_f32 v130, v130, v131
	v_cvt_pk_bf16_f32 v131, v132, v133
	v_cvt_pk_bf16_f32 v132, v196, v197
	v_cvt_pk_bf16_f32 v133, v186, v187
	global_store_dwordx4 v[176:177], v[130:133], off
	v_pk_mul_f32 v[176:177], v[66:67], v[158:159] op_sel_hi:[1,0]
	v_pk_mul_f32 v[186:187], v[68:69], v[158:159] op_sel_hi:[1,0]
	v_pk_mul_f32 v[132:133], v[72:73], v[158:159] op_sel_hi:[1,0]
	v_pk_mul_f32 v[130:131], v[70:71], v[158:159] op_sel_hi:[1,0]
	s_nop 0
	v_cvt_pk_bf16_f32 v130, v130, v131
	v_cvt_pk_bf16_f32 v131, v132, v133
	v_cvt_pk_bf16_f32 v132, v176, v177
